# GEMM MFMA order over the whole 32-MFMA segment: accumulator pairs chained, A fragment (srcB) kept stationary for 8 MFMAs, snake over B fragments
# speedup vs baseline: 1.0125x; 1.0090x over previous
.LBB0_101:
	ds_read_b128 v[154:157], v151
	ds_read_b128 v[158:161], v151 offset:1024
	ds_read_b128 v[162:165], v151 offset:2048
	ds_read_b128 v[166:169], v151 offset:3072
	ds_read_b128 v[170:173], v152
	ds_read_b128 v[174:177], v152 offset:1024
	ds_read_b128 v[188:191], v152 offset:2048
	ds_read_b128 v[192:195], v152 offset:3072
	s_add_u32 s40, s36, s38
	s_addc_u32 s41, s37, s39
	s_add_u32 s44, s40, 0x100
	s_addc_u32 s45, s41, 0
	s_add_u32 s42, s66, s38
	s_addc_u32 s43, s67, s39
	s_add_u32 s40, s40, 0x180
	s_addc_u32 s41, s41, 0
	s_cmpk_eq_i32 s38, 0x1f00
	s_cselect_b32 s41, s65, s41
	s_cselect_b32 s40, s64, s40
	s_cselect_b32 s43, s35, s43
	s_cselect_b32 s42, s34, s42
	s_cselect_b32 s45, s23, s45
	s_cselect_b32 s44, s22, s44
	s_mov_b32 m0, s57
	v_lshl_add_u64 v[178:179], v[146:147], 0, s[38:39]
	ds_read_b128 v[196:199], v153
	ds_read_b128 v[200:203], v153 offset:1024
	ds_read_b128 v[204:207], v153 offset:2048
	ds_read_b128 v[208:211], v153 offset:3072
	ds_read_b128 v[214:217], v153 offset:4096
	ds_read_b128 v[218:221], v153 offset:5120
	ds_read_b128 v[222:225], v153 offset:6144
	ds_read_b128 v[226:229], v153 offset:7168
	global_load_lds_dwordx4 v[178:179], off
	v_lshl_add_u64 v[178:179], v[148:149], 0, s[38:39]
	s_add_i32 m0, s47, 0xe000
	s_nop 0
	global_load_lds_dwordx4 v[178:179], off
	s_waitcnt vmcnt(8)
	s_waitcnt lgkmcnt(0)
	s_barrier
	s_waitcnt lgkmcnt(0)
	v_mfma_f32_16x16x32_bf16 v[126:129], v[154:157], v[196:199], v[126:129]
	v_mfma_f32_16x16x32_bf16 v[126:129], v[158:161], v[200:203], v[126:129]
	v_mfma_f32_16x16x32_bf16 v[122:125], v[166:169], v[200:203], v[122:125]
	v_mfma_f32_16x16x32_bf16 v[122:125], v[162:165], v[196:199], v[122:125]
	v_mfma_f32_16x16x32_bf16 v[114:117], v[170:173], v[196:199], v[114:117]
	v_mfma_f32_16x16x32_bf16 v[114:117], v[174:177], v[200:203], v[114:117]
	v_mfma_f32_16x16x32_bf16 v[106:109], v[192:195], v[200:203], v[106:109]
	v_mfma_f32_16x16x32_bf16 v[106:109], v[188:191], v[196:199], v[106:109]
	v_mfma_f32_16x16x32_bf16 v[90:93], v[188:191], v[204:207], v[90:93]
	v_mfma_f32_16x16x32_bf16 v[90:93], v[192:195], v[208:211], v[90:93]
	v_mfma_f32_16x16x32_bf16 v[98:101], v[174:177], v[208:211], v[98:101]
	v_mfma_f32_16x16x32_bf16 v[98:101], v[170:173], v[204:207], v[98:101]
	v_mfma_f32_16x16x32_bf16 v[110:113], v[162:165], v[204:207], v[110:113]
	v_mfma_f32_16x16x32_bf16 v[110:113], v[166:169], v[208:211], v[110:113]
	v_mfma_f32_16x16x32_bf16 v[118:121], v[158:161], v[208:211], v[118:121]
	v_mfma_f32_16x16x32_bf16 v[118:121], v[154:157], v[204:207], v[118:121]
	v_mfma_f32_16x16x32_bf16 v[102:105], v[154:157], v[214:217], v[102:105]
	v_mfma_f32_16x16x32_bf16 v[102:105], v[158:161], v[218:221], v[102:105]
	v_mfma_f32_16x16x32_bf16 v[94:97], v[166:169], v[218:221], v[94:97]
	v_mfma_f32_16x16x32_bf16 v[94:97], v[162:165], v[214:217], v[94:97]
	v_mfma_f32_16x16x32_bf16 v[82:85], v[170:173], v[214:217], v[82:85]
	v_mfma_f32_16x16x32_bf16 v[82:85], v[174:177], v[218:221], v[82:85]
	v_mfma_f32_16x16x32_bf16 v[74:77], v[192:195], v[218:221], v[74:77]
	v_mfma_f32_16x16x32_bf16 v[74:77], v[188:191], v[214:217], v[74:77]
	v_mfma_f32_16x16x32_bf16 v[66:69], v[188:191], v[222:225], v[66:69]
	v_mfma_f32_16x16x32_bf16 v[66:69], v[192:195], v[226:229], v[66:69]
	v_mfma_f32_16x16x32_bf16 v[70:73], v[174:177], v[226:229], v[70:73]
	v_mfma_f32_16x16x32_bf16 v[70:73], v[170:173], v[222:225], v[70:73]
	v_mfma_f32_16x16x32_bf16 v[78:81], v[162:165], v[222:225], v[78:81]
	v_mfma_f32_16x16x32_bf16 v[78:81], v[166:169], v[226:229], v[78:81]
	v_mfma_f32_16x16x32_bf16 v[86:89], v[158:161], v[226:229], v[86:89]
	v_mfma_f32_16x16x32_bf16 v[86:89], v[154:157], v[222:225], v[86:89]
	s_barrier
	s_add_i32 s69, s54, s3
	s_mov_b32 m0, s69
	ds_read_b128 v[196:199], v153 offset:16384
	ds_read_b128 v[200:203], v153 offset:17408
	ds_read_b128 v[204:207], v153 offset:18432
	ds_read_b128 v[208:211], v153 offset:19456
	ds_read_b128 v[214:217], v153 offset:20480
	ds_read_b128 v[218:221], v153 offset:21504
	ds_read_b128 v[222:225], v153 offset:22528
	ds_read_b128 v[226:229], v153 offset:23552
	global_load_lds_dwordx4 v136, s[42:43]
	s_add_i32 m0, s69, 0x2000
	s_add_u32 s70, s42, 0x108000
	s_addc_u32 s71, s43, 0
	s_add_i32 s69, s55, s3
	global_load_lds_dwordx4 v140, s[42:43]
	s_mov_b32 m0, s69
	s_nop 0
	global_load_lds_dwordx4 v136, s[70:71]
	s_add_i32 m0, s69, 0x2000
	s_nop 0
	global_load_lds_dwordx4 v140, s[70:71]
	s_mov_b32 m0, s47
	s_nop 0
	global_load_lds_dwordx4 v134, s[44:45]
	s_mov_b32 m0, s48
	s_nop 0
	global_load_lds_dwordx4 v138, s[44:45]
	s_waitcnt vmcnt(8)
	s_waitcnt lgkmcnt(0)
	s_barrier
	s_waitcnt lgkmcnt(0)
	v_mfma_f32_16x16x32_bf16 v[62:65], v[154:157], v[196:199], v[62:65]
	v_mfma_f32_16x16x32_bf16 v[62:65], v[158:161], v[200:203], v[62:65]
	v_mfma_f32_16x16x32_bf16 v[58:61], v[166:169], v[200:203], v[58:61]
	v_mfma_f32_16x16x32_bf16 v[58:61], v[162:165], v[196:199], v[58:61]
	v_mfma_f32_16x16x32_bf16 v[50:53], v[170:173], v[196:199], v[50:53]
	v_mfma_f32_16x16x32_bf16 v[50:53], v[174:177], v[200:203], v[50:53]
	v_mfma_f32_16x16x32_bf16 v[42:45], v[192:195], v[200:203], v[42:45]
	v_mfma_f32_16x16x32_bf16 v[42:45], v[188:191], v[196:199], v[42:45]
	v_mfma_f32_16x16x32_bf16 v[26:29], v[188:191], v[204:207], v[26:29]
	v_mfma_f32_16x16x32_bf16 v[26:29], v[192:195], v[208:211], v[26:29]
	v_mfma_f32_16x16x32_bf16 v[34:37], v[174:177], v[208:211], v[34:37]
	v_mfma_f32_16x16x32_bf16 v[34:37], v[170:173], v[204:207], v[34:37]
	v_mfma_f32_16x16x32_bf16 v[46:49], v[162:165], v[204:207], v[46:49]
	v_mfma_f32_16x16x32_bf16 v[46:49], v[166:169], v[208:211], v[46:49]
	v_mfma_f32_16x16x32_bf16 v[54:57], v[158:161], v[208:211], v[54:57]
	v_mfma_f32_16x16x32_bf16 v[54:57], v[154:157], v[204:207], v[54:57]
	v_mfma_f32_16x16x32_bf16 v[38:41], v[154:157], v[214:217], v[38:41]
	v_mfma_f32_16x16x32_bf16 v[38:41], v[158:161], v[218:221], v[38:41]
	v_mfma_f32_16x16x32_bf16 v[30:33], v[166:169], v[218:221], v[30:33]
	v_mfma_f32_16x16x32_bf16 v[30:33], v[162:165], v[214:217], v[30:33]
	v_mfma_f32_16x16x32_bf16 v[18:21], v[170:173], v[214:217], v[18:21]
	v_mfma_f32_16x16x32_bf16 v[18:21], v[174:177], v[218:221], v[18:21]
	v_mfma_f32_16x16x32_bf16 v[10:13], v[192:195], v[218:221], v[10:13]
	v_mfma_f32_16x16x32_bf16 v[10:13], v[188:191], v[214:217], v[10:13]
	v_mfma_f32_16x16x32_bf16 v[2:5], v[188:191], v[222:225], v[2:5]
	v_mfma_f32_16x16x32_bf16 v[2:5], v[192:195], v[226:229], v[2:5]
	v_mfma_f32_16x16x32_bf16 v[6:9], v[174:177], v[226:229], v[6:9]
	v_mfma_f32_16x16x32_bf16 v[6:9], v[170:173], v[222:225], v[6:9]
	v_mfma_f32_16x16x32_bf16 v[14:17], v[162:165], v[222:225], v[14:17]
	v_mfma_f32_16x16x32_bf16 v[14:17], v[166:169], v[226:229], v[14:17]
	v_mfma_f32_16x16x32_bf16 v[22:25], v[158:161], v[226:229], v[22:25]
	v_mfma_f32_16x16x32_bf16 v[22:25], v[154:157], v[222:225], v[22:25]
	s_barrier
	s_add_i32 s69, 0, 0x18000
	s_add_i32 s70, 0, 0x1c000
	v_add_u32_e32 v166, s69, v133
	v_add_u32_e32 v187, s70, v133
	ds_read_b128 v[154:157], v166
	ds_read_b128 v[158:161], v166 offset:1024
	ds_read_b128 v[162:165], v166 offset:2048
	ds_read_b128 v[166:169], v166 offset:3072
	ds_read_b128 v[170:173], v187
	ds_read_b128 v[174:177], v187 offset:1024
	ds_read_b128 v[188:191], v187 offset:2048
	ds_read_b128 v[192:195], v187 offset:3072
	s_add_u32 s44, s44, 0x108000
	s_addc_u32 s45, s45, 0
	s_mov_b32 m0, s49
	ds_read_b128 v[196:199], v153 offset:32768
	ds_read_b128 v[200:203], v153 offset:33792
	ds_read_b128 v[204:207], v153 offset:34816
	ds_read_b128 v[208:211], v153 offset:35840
	ds_read_b128 v[214:217], v153 offset:36864
	ds_read_b128 v[218:221], v153 offset:37888
	ds_read_b128 v[222:225], v153 offset:38912
	ds_read_b128 v[226:229], v153 offset:39936
	global_load_lds_dwordx4 v134, s[44:45]
	s_mov_b32 m0, s50
	s_nop 0
	global_load_lds_dwordx4 v138, s[44:45]
	s_waitcnt vmcnt(8)
	s_waitcnt lgkmcnt(0)
	s_barrier
	s_waitcnt lgkmcnt(0)
	v_mfma_f32_16x16x32_bf16 v[126:129], v[154:157], v[196:199], v[126:129]
	v_mfma_f32_16x16x32_bf16 v[126:129], v[158:161], v[200:203], v[126:129]
	v_mfma_f32_16x16x32_bf16 v[122:125], v[166:169], v[200:203], v[122:125]
	v_mfma_f32_16x16x32_bf16 v[122:125], v[162:165], v[196:199], v[122:125]
	v_mfma_f32_16x16x32_bf16 v[114:117], v[170:173], v[196:199], v[114:117]
	v_mfma_f32_16x16x32_bf16 v[114:117], v[174:177], v[200:203], v[114:117]
	v_mfma_f32_16x16x32_bf16 v[106:109], v[192:195], v[200:203], v[106:109]
	v_mfma_f32_16x16x32_bf16 v[106:109], v[188:191], v[196:199], v[106:109]
	v_mfma_f32_16x16x32_bf16 v[90:93], v[188:191], v[204:207], v[90:93]
	v_mfma_f32_16x16x32_bf16 v[90:93], v[192:195], v[208:211], v[90:93]
	v_mfma_f32_16x16x32_bf16 v[98:101], v[174:177], v[208:211], v[98:101]
	v_mfma_f32_16x16x32_bf16 v[98:101], v[170:173], v[204:207], v[98:101]
	v_mfma_f32_16x16x32_bf16 v[110:113], v[162:165], v[204:207], v[110:113]
	v_mfma_f32_16x16x32_bf16 v[110:113], v[166:169], v[208:211], v[110:113]
	v_mfma_f32_16x16x32_bf16 v[118:121], v[158:161], v[208:211], v[118:121]
	v_mfma_f32_16x16x32_bf16 v[118:121], v[154:157], v[204:207], v[118:121]
	v_mfma_f32_16x16x32_bf16 v[102:105], v[154:157], v[214:217], v[102:105]
	v_mfma_f32_16x16x32_bf16 v[102:105], v[158:161], v[218:221], v[102:105]
	v_mfma_f32_16x16x32_bf16 v[94:97], v[166:169], v[218:221], v[94:97]
	v_mfma_f32_16x16x32_bf16 v[94:97], v[162:165], v[214:217], v[94:97]
	v_mfma_f32_16x16x32_bf16 v[82:85], v[170:173], v[214:217], v[82:85]
	v_mfma_f32_16x16x32_bf16 v[82:85], v[174:177], v[218:221], v[82:85]
	v_mfma_f32_16x16x32_bf16 v[74:77], v[192:195], v[218:221], v[74:77]
	v_mfma_f32_16x16x32_bf16 v[74:77], v[188:191], v[214:217], v[74:77]
	v_mfma_f32_16x16x32_bf16 v[66:69], v[188:191], v[222:225], v[66:69]
	v_mfma_f32_16x16x32_bf16 v[66:69], v[192:195], v[226:229], v[66:69]
	v_mfma_f32_16x16x32_bf16 v[70:73], v[174:177], v[226:229], v[70:73]
	v_mfma_f32_16x16x32_bf16 v[70:73], v[170:173], v[222:225], v[70:73]
	v_mfma_f32_16x16x32_bf16 v[78:81], v[162:165], v[222:225], v[78:81]
	v_mfma_f32_16x16x32_bf16 v[78:81], v[166:169], v[226:229], v[78:81]
	v_mfma_f32_16x16x32_bf16 v[86:89], v[158:161], v[226:229], v[86:89]
	v_mfma_f32_16x16x32_bf16 v[86:89], v[154:157], v[222:225], v[86:89]
	s_barrier
	s_add_i32 s44, s69, s3
	s_add_u32 s42, s42, 0x80
	s_addc_u32 s43, s43, 0
	s_mov_b32 m0, s44
	ds_read_b128 v[196:199], v153 offset:49152
	ds_read_b128 v[200:203], v153 offset:50176
	ds_read_b128 v[204:207], v153 offset:51200
	ds_read_b128 v[208:211], v153 offset:52224
	ds_read_b128 v[214:217], v153 offset:53248
	ds_read_b128 v[218:221], v153 offset:54272
	ds_read_b128 v[222:225], v153 offset:55296
	ds_read_b128 v[226:229], v153 offset:56320
	global_load_lds_dwordx4 v136, s[42:43]
	s_add_i32 m0, s44, 0x2000
	s_add_i32 s44, s70, s3
	global_load_lds_dwordx4 v140, s[42:43]
	s_add_u32 s42, s42, 0x108000
	s_addc_u32 s43, s43, 0
	s_mov_b32 m0, s44
	s_nop 0
	global_load_lds_dwordx4 v136, s[42:43]
	s_add_i32 m0, s44, 0x2000
	s_nop 0
	global_load_lds_dwordx4 v140, s[42:43]
	s_mov_b32 m0, s52
	s_nop 0
	global_load_lds_dwordx4 v134, s[40:41]
	s_mov_b32 m0, s53
	s_nop 0
	global_load_lds_dwordx4 v138, s[40:41]
	s_waitcnt vmcnt(8)
	s_waitcnt lgkmcnt(0)
	s_barrier
	s_waitcnt lgkmcnt(0)
	v_mfma_f32_16x16x32_bf16 v[62:65], v[154:157], v[196:199], v[62:65]
	v_mfma_f32_16x16x32_bf16 v[62:65], v[158:161], v[200:203], v[62:65]
	v_mfma_f32_16x16x32_bf16 v[58:61], v[166:169], v[200:203], v[58:61]
	v_mfma_f32_16x16x32_bf16 v[58:61], v[162:165], v[196:199], v[58:61]
	v_mfma_f32_16x16x32_bf16 v[50:53], v[170:173], v[196:199], v[50:53]
	v_mfma_f32_16x16x32_bf16 v[50:53], v[174:177], v[200:203], v[50:53]
	v_mfma_f32_16x16x32_bf16 v[42:45], v[192:195], v[200:203], v[42:45]
	v_mfma_f32_16x16x32_bf16 v[42:45], v[188:191], v[196:199], v[42:45]
	v_mfma_f32_16x16x32_bf16 v[26:29], v[188:191], v[204:207], v[26:29]
	v_mfma_f32_16x16x32_bf16 v[26:29], v[192:195], v[208:211], v[26:29]
	v_mfma_f32_16x16x32_bf16 v[34:37], v[174:177], v[208:211], v[34:37]
	v_mfma_f32_16x16x32_bf16 v[34:37], v[170:173], v[204:207], v[34:37]
	v_mfma_f32_16x16x32_bf16 v[46:49], v[162:165], v[204:207], v[46:49]
	v_mfma_f32_16x16x32_bf16 v[46:49], v[166:169], v[208:211], v[46:49]
	v_mfma_f32_16x16x32_bf16 v[54:57], v[158:161], v[208:211], v[54:57]
	v_mfma_f32_16x16x32_bf16 v[54:57], v[154:157], v[204:207], v[54:57]
	v_mfma_f32_16x16x32_bf16 v[38:41], v[154:157], v[214:217], v[38:41]
	v_mfma_f32_16x16x32_bf16 v[38:41], v[158:161], v[218:221], v[38:41]
	v_mfma_f32_16x16x32_bf16 v[30:33], v[166:169], v[218:221], v[30:33]
	v_mfma_f32_16x16x32_bf16 v[30:33], v[162:165], v[214:217], v[30:33]
	v_mfma_f32_16x16x32_bf16 v[18:21], v[170:173], v[214:217], v[18:21]
	v_mfma_f32_16x16x32_bf16 v[18:21], v[174:177], v[218:221], v[18:21]
	v_mfma_f32_16x16x32_bf16 v[10:13], v[192:195], v[218:221], v[10:13]
	v_mfma_f32_16x16x32_bf16 v[10:13], v[188:191], v[214:217], v[10:13]
	v_mfma_f32_16x16x32_bf16 v[2:5], v[188:191], v[222:225], v[2:5]
	v_mfma_f32_16x16x32_bf16 v[2:5], v[192:195], v[226:229], v[2:5]
	v_mfma_f32_16x16x32_bf16 v[6:9], v[174:177], v[226:229], v[6:9]
	v_mfma_f32_16x16x32_bf16 v[6:9], v[170:173], v[222:225], v[6:9]
	v_mfma_f32_16x16x32_bf16 v[14:17], v[162:165], v[222:225], v[14:17]
	v_mfma_f32_16x16x32_bf16 v[14:17], v[166:169], v[226:229], v[14:17]
	v_mfma_f32_16x16x32_bf16 v[22:25], v[158:161], v[226:229], v[22:25]
	v_mfma_f32_16x16x32_bf16 v[22:25], v[154:157], v[222:225], v[22:25]
	s_barrier
	s_add_i32 s68, s68, 2
	s_add_u32 s38, s38, 0x100
	s_addc_u32 s39, s39, 0
	s_cmp_gt_u32 s68, 61
	s_cbranch_scc0 .LBB0_101
	s_and_b64 vcc, exec, s[20:21]
	s_cbranch_vccz .LBB0_104
	s_barrier

.LBB0_235:
	ds_read_b128 v[156:159], v150
	ds_read_b128 v[160:163], v150 offset:1024
	ds_read_b128 v[164:167], v150 offset:2048
	ds_read_b128 v[168:171], v150 offset:3072
	ds_read_b128 v[172:175], v151
	ds_read_b128 v[176:179], v151 offset:1024
	ds_read_b128 v[180:183], v151 offset:2048
	ds_read_b128 v[184:187], v151 offset:3072
	s_add_u32 s36, s4, s34
	s_addc_u32 s37, s5, s35
	s_add_u32 s40, s36, 0x100
	s_addc_u32 s41, s37, 0
	s_add_u32 s38, s62, s34
	s_addc_u32 s39, s63, s35
	s_add_u32 s36, s36, 0x180
	s_addc_u32 s37, s37, 0
	s_cmpk_eq_i32 s34, 0x1f00
	s_cselect_b32 s37, s61, s37
	s_cselect_b32 s36, s60, s36
	s_cselect_b32 s39, s31, s39
	s_cselect_b32 s38, s30, s38
	s_cselect_b32 s41, s23, s41
	s_cselect_b32 s40, s22, s40
	s_mov_b32 m0, s46
	v_lshl_add_u64 v[222:223], v[146:147], 0, s[34:35]
	ds_read_b128 v[188:191], v152
	ds_read_b128 v[192:195], v152 offset:1024
	ds_read_b128 v[196:199], v152 offset:2048
	ds_read_b128 v[200:203], v152 offset:3072
	ds_read_b128 v[204:207], v152 offset:4096
	ds_read_b128 v[208:211], v152 offset:5120
	ds_read_b128 v[214:217], v152 offset:6144
	ds_read_b128 v[218:221], v152 offset:7168
	global_load_lds_dwordx4 v[222:223], off
	v_lshl_add_u64 v[222:223], v[148:149], 0, s[34:35]
	s_mov_b32 m0, s47
	s_nop 0
	global_load_lds_dwordx4 v[222:223], off
	s_waitcnt vmcnt(8)
	s_waitcnt lgkmcnt(0)
	s_barrier
	s_waitcnt lgkmcnt(0)
	v_mfma_f32_16x16x32_bf16 v[126:129], v[156:159], v[188:191], v[126:129]
	v_mfma_f32_16x16x32_bf16 v[126:129], v[160:163], v[192:195], v[126:129]
	v_mfma_f32_16x16x32_bf16 v[122:125], v[168:171], v[192:195], v[122:125]
	v_mfma_f32_16x16x32_bf16 v[122:125], v[164:167], v[188:191], v[122:125]
	v_mfma_f32_16x16x32_bf16 v[118:121], v[172:175], v[188:191], v[118:121]
	v_mfma_f32_16x16x32_bf16 v[118:121], v[176:179], v[192:195], v[118:121]
	v_mfma_f32_16x16x32_bf16 v[114:117], v[184:187], v[192:195], v[114:117]
	v_mfma_f32_16x16x32_bf16 v[114:117], v[180:183], v[188:191], v[114:117]
	v_mfma_f32_16x16x32_bf16 v[98:101], v[180:183], v[196:199], v[98:101]
	v_mfma_f32_16x16x32_bf16 v[98:101], v[184:187], v[200:203], v[98:101]
	v_mfma_f32_16x16x32_bf16 v[102:105], v[176:179], v[200:203], v[102:105]
	v_mfma_f32_16x16x32_bf16 v[102:105], v[172:175], v[196:199], v[102:105]
	v_mfma_f32_16x16x32_bf16 v[106:109], v[164:167], v[196:199], v[106:109]
	v_mfma_f32_16x16x32_bf16 v[106:109], v[168:171], v[200:203], v[106:109]
	v_mfma_f32_16x16x32_bf16 v[110:113], v[160:163], v[200:203], v[110:113]
	v_mfma_f32_16x16x32_bf16 v[110:113], v[156:159], v[196:199], v[110:113]
	v_mfma_f32_16x16x32_bf16 v[94:97], v[156:159], v[204:207], v[94:97]
	v_mfma_f32_16x16x32_bf16 v[94:97], v[160:163], v[208:211], v[94:97]
	v_mfma_f32_16x16x32_bf16 v[90:93], v[168:171], v[208:211], v[90:93]
	v_mfma_f32_16x16x32_bf16 v[90:93], v[164:167], v[204:207], v[90:93]
	v_mfma_f32_16x16x32_bf16 v[86:89], v[172:175], v[204:207], v[86:89]
	v_mfma_f32_16x16x32_bf16 v[86:89], v[176:179], v[208:211], v[86:89]
	v_mfma_f32_16x16x32_bf16 v[82:85], v[184:187], v[208:211], v[82:85]
	v_mfma_f32_16x16x32_bf16 v[82:85], v[180:183], v[204:207], v[82:85]
	v_mfma_f32_16x16x32_bf16 v[66:69], v[180:183], v[214:217], v[66:69]
	v_mfma_f32_16x16x32_bf16 v[66:69], v[184:187], v[218:221], v[66:69]
	v_mfma_f32_16x16x32_bf16 v[70:73], v[176:179], v[218:221], v[70:73]
	v_mfma_f32_16x16x32_bf16 v[70:73], v[172:175], v[214:217], v[70:73]
	v_mfma_f32_16x16x32_bf16 v[74:77], v[164:167], v[214:217], v[74:77]
	v_mfma_f32_16x16x32_bf16 v[74:77], v[168:171], v[218:221], v[74:77]
	v_mfma_f32_16x16x32_bf16 v[78:81], v[160:163], v[218:221], v[78:81]
	v_mfma_f32_16x16x32_bf16 v[78:81], v[156:159], v[214:217], v[78:81]
	s_barrier
	s_mov_b32 m0, s48
	s_add_u32 s66, s38, 0x108000
	ds_read_b128 v[188:191], v152 offset:16384
	ds_read_b128 v[192:195], v152 offset:17408
	ds_read_b128 v[196:199], v152 offset:18432
	ds_read_b128 v[200:203], v152 offset:19456
	ds_read_b128 v[204:207], v152 offset:20480
	ds_read_b128 v[208:211], v152 offset:21504
	ds_read_b128 v[214:217], v152 offset:22528
	ds_read_b128 v[218:221], v152 offset:23552
	global_load_lds_dwordx4 v132, s[38:39]
	s_mov_b32 m0, s49
	s_addc_u32 s67, s39, 0
	global_load_lds_dwordx4 v136, s[38:39]
	s_mov_b32 m0, s50
	s_nop 0
	global_load_lds_dwordx4 v132, s[66:67]
	s_mov_b32 m0, s51
	s_nop 0
	global_load_lds_dwordx4 v136, s[66:67]
	s_mov_b32 m0, s3
	s_nop 0
	global_load_lds_dwordx4 v130, s[40:41]
	s_mov_b32 m0, s33
	s_nop 0
	global_load_lds_dwordx4 v134, s[40:41]
	s_waitcnt vmcnt(8)
	s_waitcnt lgkmcnt(0)
	s_barrier
	s_waitcnt lgkmcnt(0)
	v_mfma_f32_16x16x32_bf16 v[62:65], v[156:159], v[188:191], v[62:65]
	v_mfma_f32_16x16x32_bf16 v[62:65], v[160:163], v[192:195], v[62:65]
	v_mfma_f32_16x16x32_bf16 v[58:61], v[168:171], v[192:195], v[58:61]
	v_mfma_f32_16x16x32_bf16 v[58:61], v[164:167], v[188:191], v[58:61]
	v_mfma_f32_16x16x32_bf16 v[54:57], v[172:175], v[188:191], v[54:57]
	v_mfma_f32_16x16x32_bf16 v[54:57], v[176:179], v[192:195], v[54:57]
	v_mfma_f32_16x16x32_bf16 v[50:53], v[184:187], v[192:195], v[50:53]
	v_mfma_f32_16x16x32_bf16 v[50:53], v[180:183], v[188:191], v[50:53]
	v_mfma_f32_16x16x32_bf16 v[34:37], v[180:183], v[196:199], v[34:37]
	v_mfma_f32_16x16x32_bf16 v[34:37], v[184:187], v[200:203], v[34:37]
	v_mfma_f32_16x16x32_bf16 v[38:41], v[176:179], v[200:203], v[38:41]
	v_mfma_f32_16x16x32_bf16 v[38:41], v[172:175], v[196:199], v[38:41]
	v_mfma_f32_16x16x32_bf16 v[42:45], v[164:167], v[196:199], v[42:45]
	v_mfma_f32_16x16x32_bf16 v[42:45], v[168:171], v[200:203], v[42:45]
	v_mfma_f32_16x16x32_bf16 v[46:49], v[160:163], v[200:203], v[46:49]
	v_mfma_f32_16x16x32_bf16 v[46:49], v[156:159], v[196:199], v[46:49]
	v_mfma_f32_16x16x32_bf16 v[30:33], v[156:159], v[204:207], v[30:33]
	v_mfma_f32_16x16x32_bf16 v[30:33], v[160:163], v[208:211], v[30:33]
	v_mfma_f32_16x16x32_bf16 v[26:29], v[168:171], v[208:211], v[26:29]
	v_mfma_f32_16x16x32_bf16 v[26:29], v[164:167], v[204:207], v[26:29]
	v_mfma_f32_16x16x32_bf16 v[22:25], v[172:175], v[204:207], v[22:25]
	v_mfma_f32_16x16x32_bf16 v[22:25], v[176:179], v[208:211], v[22:25]
	v_mfma_f32_16x16x32_bf16 v[18:21], v[184:187], v[208:211], v[18:21]
	v_mfma_f32_16x16x32_bf16 v[18:21], v[180:183], v[204:207], v[18:21]
	v_mfma_f32_16x16x32_bf16 v[2:5], v[180:183], v[214:217], v[2:5]
	v_mfma_f32_16x16x32_bf16 v[2:5], v[184:187], v[218:221], v[2:5]
	v_mfma_f32_16x16x32_bf16 v[6:9], v[176:179], v[218:221], v[6:9]
	v_mfma_f32_16x16x32_bf16 v[6:9], v[172:175], v[214:217], v[6:9]
	v_mfma_f32_16x16x32_bf16 v[10:13], v[164:167], v[214:217], v[10:13]
	v_mfma_f32_16x16x32_bf16 v[10:13], v[168:171], v[218:221], v[10:13]
	v_mfma_f32_16x16x32_bf16 v[14:17], v[160:163], v[218:221], v[14:17]
	v_mfma_f32_16x16x32_bf16 v[14:17], v[156:159], v[214:217], v[14:17]
	s_barrier
	ds_read_b128 v[156:159], v153
	ds_read_b128 v[160:163], v153 offset:1024
	ds_read_b128 v[164:167], v153 offset:2048
	ds_read_b128 v[168:171], v153 offset:3072
	ds_read_b128 v[172:175], v154
	ds_read_b128 v[176:179], v154 offset:1024
	ds_read_b128 v[180:183], v154 offset:2048
	ds_read_b128 v[184:187], v154 offset:3072
	s_add_u32 s40, s40, 0x108000
	s_addc_u32 s41, s41, 0
	s_mov_b32 m0, s42
	ds_read_b128 v[188:191], v152 offset:32768
	ds_read_b128 v[192:195], v152 offset:33792
	ds_read_b128 v[196:199], v152 offset:34816
	ds_read_b128 v[200:203], v152 offset:35840
	ds_read_b128 v[204:207], v152 offset:36864
	ds_read_b128 v[208:211], v152 offset:37888
	ds_read_b128 v[214:217], v152 offset:38912
	ds_read_b128 v[218:221], v152 offset:39936
	global_load_lds_dwordx4 v130, s[40:41]
	s_mov_b32 m0, s43
	s_nop 0
	global_load_lds_dwordx4 v134, s[40:41]
	s_waitcnt vmcnt(8)
	s_waitcnt lgkmcnt(0)
	s_barrier
	s_waitcnt lgkmcnt(0)
	v_mfma_f32_16x16x32_bf16 v[126:129], v[156:159], v[188:191], v[126:129]
	v_mfma_f32_16x16x32_bf16 v[126:129], v[160:163], v[192:195], v[126:129]
	v_mfma_f32_16x16x32_bf16 v[122:125], v[168:171], v[192:195], v[122:125]
	v_mfma_f32_16x16x32_bf16 v[122:125], v[164:167], v[188:191], v[122:125]
	v_mfma_f32_16x16x32_bf16 v[118:121], v[172:175], v[188:191], v[118:121]
	v_mfma_f32_16x16x32_bf16 v[118:121], v[176:179], v[192:195], v[118:121]
	v_mfma_f32_16x16x32_bf16 v[114:117], v[184:187], v[192:195], v[114:117]
	v_mfma_f32_16x16x32_bf16 v[114:117], v[180:183], v[188:191], v[114:117]
	v_mfma_f32_16x16x32_bf16 v[98:101], v[180:183], v[196:199], v[98:101]
	v_mfma_f32_16x16x32_bf16 v[98:101], v[184:187], v[200:203], v[98:101]
	v_mfma_f32_16x16x32_bf16 v[102:105], v[176:179], v[200:203], v[102:105]
	v_mfma_f32_16x16x32_bf16 v[102:105], v[172:175], v[196:199], v[102:105]
	v_mfma_f32_16x16x32_bf16 v[106:109], v[164:167], v[196:199], v[106:109]
	v_mfma_f32_16x16x32_bf16 v[106:109], v[168:171], v[200:203], v[106:109]
	v_mfma_f32_16x16x32_bf16 v[110:113], v[160:163], v[200:203], v[110:113]
	v_mfma_f32_16x16x32_bf16 v[110:113], v[156:159], v[196:199], v[110:113]
	v_mfma_f32_16x16x32_bf16 v[94:97], v[156:159], v[204:207], v[94:97]
	v_mfma_f32_16x16x32_bf16 v[94:97], v[160:163], v[208:211], v[94:97]
	v_mfma_f32_16x16x32_bf16 v[90:93], v[168:171], v[208:211], v[90:93]
	v_mfma_f32_16x16x32_bf16 v[90:93], v[164:167], v[204:207], v[90:93]
	v_mfma_f32_16x16x32_bf16 v[86:89], v[172:175], v[204:207], v[86:89]
	v_mfma_f32_16x16x32_bf16 v[86:89], v[176:179], v[208:211], v[86:89]
	v_mfma_f32_16x16x32_bf16 v[82:85], v[184:187], v[208:211], v[82:85]
	v_mfma_f32_16x16x32_bf16 v[82:85], v[180:183], v[204:207], v[82:85]
	v_mfma_f32_16x16x32_bf16 v[66:69], v[180:183], v[214:217], v[66:69]
	v_mfma_f32_16x16x32_bf16 v[66:69], v[184:187], v[218:221], v[66:69]
	v_mfma_f32_16x16x32_bf16 v[70:73], v[176:179], v[218:221], v[70:73]
	v_mfma_f32_16x16x32_bf16 v[70:73], v[172:175], v[214:217], v[70:73]
	v_mfma_f32_16x16x32_bf16 v[74:77], v[164:167], v[214:217], v[74:77]
	v_mfma_f32_16x16x32_bf16 v[74:77], v[168:171], v[218:221], v[74:77]
	v_mfma_f32_16x16x32_bf16 v[78:81], v[160:163], v[218:221], v[78:81]
	v_mfma_f32_16x16x32_bf16 v[78:81], v[156:159], v[214:217], v[78:81]
	s_barrier
	s_mov_b32 m0, s53
	s_add_u32 s38, s38, 0x80
	s_addc_u32 s39, s39, 0
	ds_read_b128 v[188:191], v152 offset:49152
	ds_read_b128 v[192:195], v152 offset:50176
	ds_read_b128 v[196:199], v152 offset:51200
	ds_read_b128 v[200:203], v152 offset:52224
	ds_read_b128 v[204:207], v152 offset:53248
	ds_read_b128 v[208:211], v152 offset:54272
	ds_read_b128 v[214:217], v152 offset:55296
	ds_read_b128 v[218:221], v152 offset:56320
	global_load_lds_dwordx4 v132, s[38:39]
	s_mov_b32 m0, s54
	s_add_i32 s40, s52, s2
	global_load_lds_dwordx4 v136, s[38:39]
	s_add_u32 s38, s38, 0x108000
	s_addc_u32 s39, s39, 0
	s_mov_b32 m0, s40
	s_nop 0
	global_load_lds_dwordx4 v132, s[38:39]
	s_add_i32 m0, s40, 0x2000
	s_nop 0
	global_load_lds_dwordx4 v136, s[38:39]
	s_mov_b32 m0, s44
	s_nop 0
	global_load_lds_dwordx4 v130, s[36:37]
	s_mov_b32 m0, s45
	s_nop 0
	global_load_lds_dwordx4 v134, s[36:37]
	s_waitcnt vmcnt(8)
	s_waitcnt lgkmcnt(0)
	s_barrier
	s_waitcnt lgkmcnt(0)
	v_mfma_f32_16x16x32_bf16 v[62:65], v[156:159], v[188:191], v[62:65]
	v_mfma_f32_16x16x32_bf16 v[62:65], v[160:163], v[192:195], v[62:65]
	v_mfma_f32_16x16x32_bf16 v[58:61], v[168:171], v[192:195], v[58:61]
	v_mfma_f32_16x16x32_bf16 v[58:61], v[164:167], v[188:191], v[58:61]
	v_mfma_f32_16x16x32_bf16 v[54:57], v[172:175], v[188:191], v[54:57]
	v_mfma_f32_16x16x32_bf16 v[54:57], v[176:179], v[192:195], v[54:57]
	v_mfma_f32_16x16x32_bf16 v[50:53], v[184:187], v[192:195], v[50:53]
	v_mfma_f32_16x16x32_bf16 v[50:53], v[180:183], v[188:191], v[50:53]
	v_mfma_f32_16x16x32_bf16 v[34:37], v[180:183], v[196:199], v[34:37]
	v_mfma_f32_16x16x32_bf16 v[34:37], v[184:187], v[200:203], v[34:37]
	v_mfma_f32_16x16x32_bf16 v[38:41], v[176:179], v[200:203], v[38:41]
	v_mfma_f32_16x16x32_bf16 v[38:41], v[172:175], v[196:199], v[38:41]
	v_mfma_f32_16x16x32_bf16 v[42:45], v[164:167], v[196:199], v[42:45]
	v_mfma_f32_16x16x32_bf16 v[42:45], v[168:171], v[200:203], v[42:45]
	v_mfma_f32_16x16x32_bf16 v[46:49], v[160:163], v[200:203], v[46:49]
	v_mfma_f32_16x16x32_bf16 v[46:49], v[156:159], v[196:199], v[46:49]
	v_mfma_f32_16x16x32_bf16 v[30:33], v[156:159], v[204:207], v[30:33]
	v_mfma_f32_16x16x32_bf16 v[30:33], v[160:163], v[208:211], v[30:33]
	v_mfma_f32_16x16x32_bf16 v[26:29], v[168:171], v[208:211], v[26:29]
	v_mfma_f32_16x16x32_bf16 v[26:29], v[164:167], v[204:207], v[26:29]
	v_mfma_f32_16x16x32_bf16 v[22:25], v[172:175], v[204:207], v[22:25]
	v_mfma_f32_16x16x32_bf16 v[22:25], v[176:179], v[208:211], v[22:25]
	v_mfma_f32_16x16x32_bf16 v[18:21], v[184:187], v[208:211], v[18:21]
	v_mfma_f32_16x16x32_bf16 v[18:21], v[180:183], v[204:207], v[18:21]
	v_mfma_f32_16x16x32_bf16 v[2:5], v[180:183], v[214:217], v[2:5]
	v_mfma_f32_16x16x32_bf16 v[2:5], v[184:187], v[218:221], v[2:5]
	v_mfma_f32_16x16x32_bf16 v[6:9], v[176:179], v[218:221], v[6:9]
	v_mfma_f32_16x16x32_bf16 v[6:9], v[172:175], v[214:217], v[6:9]
	v_mfma_f32_16x16x32_bf16 v[10:13], v[164:167], v[214:217], v[10:13]
	v_mfma_f32_16x16x32_bf16 v[10:13], v[168:171], v[218:221], v[10:13]
	v_mfma_f32_16x16x32_bf16 v[14:17], v[160:163], v[218:221], v[14:17]
	v_mfma_f32_16x16x32_bf16 v[14:17], v[156:159], v[214:217], v[14:17]
	s_barrier
	s_add_i32 s64, s64, 2
	s_add_u32 s34, s34, 0x100
	s_addc_u32 s35, s35, 0
	s_cmp_gt_u32 s64, 61
	s_cbranch_scc0 .LBB0_235
	s_and_b64 vcc, exec, s[20:21]
	s_cbranch_vccz .LBB0_238
	s_barrier

.LBB0_434:
	ds_read_b128 v[134:137], v204
	ds_read_b128 v[138:141], v204 offset:1024
	ds_read_b128 v[142:145], v204 offset:2048
	ds_read_b128 v[146:149], v204 offset:3072
	ds_read_b128 v[150:153], v205
	ds_read_b128 v[154:157], v205 offset:1024
	ds_read_b128 v[158:161], v205 offset:2048
	ds_read_b128 v[162:165], v205 offset:3072
	s_add_u32 s34, s22, s30
	s_addc_u32 s35, s23, s31
	s_add_u32 s38, s34, 0x100
	s_addc_u32 s39, s35, 0
	s_add_u32 s36, s60, s30
	s_addc_u32 s37, s61, s31
	s_add_u32 s34, s34, 0x180
	s_addc_u32 s35, s35, 0
	s_cmpk_eq_i32 s30, 0xb00
	s_cselect_b32 s35, s59, s35
	s_cselect_b32 s34, s58, s34
	s_cselect_b32 s37, s21, s37
	s_cselect_b32 s36, s20, s36
	s_cselect_b32 s39, s17, s39
	s_cselect_b32 s38, s16, s38
	v_lshl_add_u64 v[200:201], v[130:131], 0, s[30:31]
	s_add_i32 m0, s3, 0xc000
	ds_read_b128 v[166:169], v206
	ds_read_b128 v[170:173], v206 offset:1024
	ds_read_b128 v[174:177], v206 offset:2048
	ds_read_b128 v[178:181], v206 offset:3072
	ds_read_b128 v[182:185], v206 offset:4096
	ds_read_b128 v[208:211], v206 offset:5120
	ds_read_b128 v[214:217], v206 offset:6144
	ds_read_b128 v[218:221], v206 offset:7168
	global_load_lds_dwordx4 v[200:201], off
	v_lshl_add_u64 v[200:201], v[132:133], 0, s[30:31]
	s_add_i32 m0, s3, 0xe000
	s_nop 0
	global_load_lds_dwordx4 v[200:201], off
	s_waitcnt vmcnt(8)
	s_waitcnt lgkmcnt(0)
	s_barrier
	s_waitcnt lgkmcnt(0)
	v_mfma_f32_16x16x32_bf16 v[126:129], v[134:137], v[166:169], v[126:129]
	v_mfma_f32_16x16x32_bf16 v[126:129], v[138:141], v[170:173], v[126:129]
	v_mfma_f32_16x16x32_bf16 v[122:125], v[146:149], v[170:173], v[122:125]
	v_mfma_f32_16x16x32_bf16 v[122:125], v[142:145], v[166:169], v[122:125]
	v_mfma_f32_16x16x32_bf16 v[118:121], v[150:153], v[166:169], v[118:121]
	v_mfma_f32_16x16x32_bf16 v[118:121], v[154:157], v[170:173], v[118:121]
	v_mfma_f32_16x16x32_bf16 v[114:117], v[162:165], v[170:173], v[114:117]
	v_mfma_f32_16x16x32_bf16 v[114:117], v[158:161], v[166:169], v[114:117]
	v_mfma_f32_16x16x32_bf16 v[98:101], v[158:161], v[174:177], v[98:101]
	v_mfma_f32_16x16x32_bf16 v[98:101], v[162:165], v[178:181], v[98:101]
	v_mfma_f32_16x16x32_bf16 v[102:105], v[154:157], v[178:181], v[102:105]
	v_mfma_f32_16x16x32_bf16 v[102:105], v[150:153], v[174:177], v[102:105]
	v_mfma_f32_16x16x32_bf16 v[106:109], v[142:145], v[174:177], v[106:109]
	v_mfma_f32_16x16x32_bf16 v[106:109], v[146:149], v[178:181], v[106:109]
	v_mfma_f32_16x16x32_bf16 v[110:113], v[138:141], v[178:181], v[110:113]
	v_mfma_f32_16x16x32_bf16 v[110:113], v[134:137], v[174:177], v[110:113]
	v_mfma_f32_16x16x32_bf16 v[94:97], v[134:137], v[182:185], v[94:97]
	v_mfma_f32_16x16x32_bf16 v[94:97], v[138:141], v[208:211], v[94:97]
	v_mfma_f32_16x16x32_bf16 v[90:93], v[146:149], v[208:211], v[90:93]
	v_mfma_f32_16x16x32_bf16 v[90:93], v[142:145], v[182:185], v[90:93]
	v_mfma_f32_16x16x32_bf16 v[86:89], v[150:153], v[182:185], v[86:89]
	v_mfma_f32_16x16x32_bf16 v[86:89], v[154:157], v[208:211], v[86:89]
	v_mfma_f32_16x16x32_bf16 v[82:85], v[162:165], v[208:211], v[82:85]
	v_mfma_f32_16x16x32_bf16 v[82:85], v[158:161], v[182:185], v[82:85]
	v_mfma_f32_16x16x32_bf16 v[66:69], v[158:161], v[214:217], v[66:69]
	v_mfma_f32_16x16x32_bf16 v[66:69], v[162:165], v[218:221], v[66:69]
	v_mfma_f32_16x16x32_bf16 v[70:73], v[154:157], v[218:221], v[70:73]
	v_mfma_f32_16x16x32_bf16 v[70:73], v[150:153], v[214:217], v[70:73]
	v_mfma_f32_16x16x32_bf16 v[74:77], v[142:145], v[214:217], v[74:77]
	v_mfma_f32_16x16x32_bf16 v[74:77], v[146:149], v[218:221], v[74:77]
	v_mfma_f32_16x16x32_bf16 v[78:81], v[138:141], v[218:221], v[78:81]
	v_mfma_f32_16x16x32_bf16 v[78:81], v[134:137], v[214:217], v[78:81]
	s_barrier
	s_add_i32 s63, s52, s2
	s_mov_b32 m0, s63
	ds_read_b128 v[166:169], v206 offset:16384
	ds_read_b128 v[170:173], v206 offset:17408
	ds_read_b128 v[174:177], v206 offset:18432
	ds_read_b128 v[178:181], v206 offset:19456
	ds_read_b128 v[182:185], v206 offset:20480
	ds_read_b128 v[208:211], v206 offset:21504
	ds_read_b128 v[214:217], v206 offset:22528
	ds_read_b128 v[218:221], v206 offset:23552
	global_load_lds_dwordx4 v188, s[36:37]
	s_add_i32 m0, s63, 0x2000
	s_add_u32 s64, s36, 0x68000
	s_addc_u32 s65, s37, 0
	s_add_i32 s63, s53, s2
	global_load_lds_dwordx4 v192, s[36:37]
	s_mov_b32 m0, s63
	s_nop 0
	global_load_lds_dwordx4 v188, s[64:65]
	s_add_i32 m0, s63, 0x2000
	s_nop 0
	global_load_lds_dwordx4 v192, s[64:65]
	s_mov_b32 m0, s3
	s_nop 0
	global_load_lds_dwordx4 v186, s[38:39]
	s_mov_b32 m0, s33
	s_nop 0
	global_load_lds_dwordx4 v190, s[38:39]
	s_waitcnt vmcnt(8)
	s_waitcnt lgkmcnt(0)
	s_barrier
	s_waitcnt lgkmcnt(0)
	v_mfma_f32_16x16x32_bf16 v[62:65], v[134:137], v[166:169], v[62:65]
	v_mfma_f32_16x16x32_bf16 v[62:65], v[138:141], v[170:173], v[62:65]
	v_mfma_f32_16x16x32_bf16 v[58:61], v[146:149], v[170:173], v[58:61]
	v_mfma_f32_16x16x32_bf16 v[58:61], v[142:145], v[166:169], v[58:61]
	v_mfma_f32_16x16x32_bf16 v[54:57], v[150:153], v[166:169], v[54:57]
	v_mfma_f32_16x16x32_bf16 v[54:57], v[154:157], v[170:173], v[54:57]
	v_mfma_f32_16x16x32_bf16 v[50:53], v[162:165], v[170:173], v[50:53]
	v_mfma_f32_16x16x32_bf16 v[50:53], v[158:161], v[166:169], v[50:53]
	v_mfma_f32_16x16x32_bf16 v[34:37], v[158:161], v[174:177], v[34:37]
	v_mfma_f32_16x16x32_bf16 v[34:37], v[162:165], v[178:181], v[34:37]
	v_mfma_f32_16x16x32_bf16 v[38:41], v[154:157], v[178:181], v[38:41]
	v_mfma_f32_16x16x32_bf16 v[38:41], v[150:153], v[174:177], v[38:41]
	v_mfma_f32_16x16x32_bf16 v[42:45], v[142:145], v[174:177], v[42:45]
	v_mfma_f32_16x16x32_bf16 v[42:45], v[146:149], v[178:181], v[42:45]
	v_mfma_f32_16x16x32_bf16 v[46:49], v[138:141], v[178:181], v[46:49]
	v_mfma_f32_16x16x32_bf16 v[46:49], v[134:137], v[174:177], v[46:49]
	v_mfma_f32_16x16x32_bf16 v[30:33], v[134:137], v[182:185], v[30:33]
	v_mfma_f32_16x16x32_bf16 v[30:33], v[138:141], v[208:211], v[30:33]
	v_mfma_f32_16x16x32_bf16 v[26:29], v[146:149], v[208:211], v[26:29]
	v_mfma_f32_16x16x32_bf16 v[26:29], v[142:145], v[182:185], v[26:29]
	v_mfma_f32_16x16x32_bf16 v[22:25], v[150:153], v[182:185], v[22:25]
	v_mfma_f32_16x16x32_bf16 v[22:25], v[154:157], v[208:211], v[22:25]
	v_mfma_f32_16x16x32_bf16 v[18:21], v[162:165], v[208:211], v[18:21]
	v_mfma_f32_16x16x32_bf16 v[18:21], v[158:161], v[182:185], v[18:21]
	v_mfma_f32_16x16x32_bf16 v[2:5], v[158:161], v[214:217], v[2:5]
	v_mfma_f32_16x16x32_bf16 v[2:5], v[162:165], v[218:221], v[2:5]
	v_mfma_f32_16x16x32_bf16 v[6:9], v[154:157], v[218:221], v[6:9]
	v_mfma_f32_16x16x32_bf16 v[6:9], v[150:153], v[214:217], v[6:9]
	v_mfma_f32_16x16x32_bf16 v[10:13], v[142:145], v[214:217], v[10:13]
	v_mfma_f32_16x16x32_bf16 v[10:13], v[146:149], v[218:221], v[10:13]
	v_mfma_f32_16x16x32_bf16 v[14:17], v[138:141], v[218:221], v[14:17]
	v_mfma_f32_16x16x32_bf16 v[14:17], v[134:137], v[214:217], v[14:17]
	s_barrier
	s_add_i32 s63, 0, 0x18000
	s_add_i32 s64, 0, 0x1c000
	v_add_u32_e32 v146, s63, v202
	v_add_u32_e32 v162, s64, v202
	ds_read_b128 v[134:137], v146
	ds_read_b128 v[138:141], v146 offset:1024
	ds_read_b128 v[142:145], v146 offset:2048
	ds_read_b128 v[146:149], v146 offset:3072
	ds_read_b128 v[150:153], v162
	ds_read_b128 v[154:157], v162 offset:1024
	ds_read_b128 v[158:161], v162 offset:2048
	ds_read_b128 v[162:165], v162 offset:3072
	s_add_u32 s38, s38, 0x188000
	s_addc_u32 s39, s39, 0
	s_mov_b32 m0, s40
	ds_read_b128 v[166:169], v206 offset:32768
	ds_read_b128 v[170:173], v206 offset:33792
	ds_read_b128 v[174:177], v206 offset:34816
	ds_read_b128 v[178:181], v206 offset:35840
	ds_read_b128 v[182:185], v206 offset:36864
	ds_read_b128 v[208:211], v206 offset:37888
	ds_read_b128 v[214:217], v206 offset:38912
	ds_read_b128 v[218:221], v206 offset:39936
	global_load_lds_dwordx4 v186, s[38:39]
	s_mov_b32 m0, s41
	s_nop 0
	global_load_lds_dwordx4 v190, s[38:39]
	s_waitcnt vmcnt(8)
	s_waitcnt lgkmcnt(0)
	s_barrier
	s_waitcnt lgkmcnt(0)
	v_mfma_f32_16x16x32_bf16 v[126:129], v[134:137], v[166:169], v[126:129]
	v_mfma_f32_16x16x32_bf16 v[126:129], v[138:141], v[170:173], v[126:129]
	v_mfma_f32_16x16x32_bf16 v[122:125], v[146:149], v[170:173], v[122:125]
	v_mfma_f32_16x16x32_bf16 v[122:125], v[142:145], v[166:169], v[122:125]
	v_mfma_f32_16x16x32_bf16 v[118:121], v[150:153], v[166:169], v[118:121]
	v_mfma_f32_16x16x32_bf16 v[118:121], v[154:157], v[170:173], v[118:121]
	v_mfma_f32_16x16x32_bf16 v[114:117], v[162:165], v[170:173], v[114:117]
	v_mfma_f32_16x16x32_bf16 v[114:117], v[158:161], v[166:169], v[114:117]
	v_mfma_f32_16x16x32_bf16 v[98:101], v[158:161], v[174:177], v[98:101]
	v_mfma_f32_16x16x32_bf16 v[98:101], v[162:165], v[178:181], v[98:101]
	v_mfma_f32_16x16x32_bf16 v[102:105], v[154:157], v[178:181], v[102:105]
	v_mfma_f32_16x16x32_bf16 v[102:105], v[150:153], v[174:177], v[102:105]
	v_mfma_f32_16x16x32_bf16 v[106:109], v[142:145], v[174:177], v[106:109]
	v_mfma_f32_16x16x32_bf16 v[106:109], v[146:149], v[178:181], v[106:109]
	v_mfma_f32_16x16x32_bf16 v[110:113], v[138:141], v[178:181], v[110:113]
	v_mfma_f32_16x16x32_bf16 v[110:113], v[134:137], v[174:177], v[110:113]
	v_mfma_f32_16x16x32_bf16 v[94:97], v[134:137], v[182:185], v[94:97]
	v_mfma_f32_16x16x32_bf16 v[94:97], v[138:141], v[208:211], v[94:97]
	v_mfma_f32_16x16x32_bf16 v[90:93], v[146:149], v[208:211], v[90:93]
	v_mfma_f32_16x16x32_bf16 v[90:93], v[142:145], v[182:185], v[90:93]
	v_mfma_f32_16x16x32_bf16 v[86:89], v[150:153], v[182:185], v[86:89]
	v_mfma_f32_16x16x32_bf16 v[86:89], v[154:157], v[208:211], v[86:89]
	v_mfma_f32_16x16x32_bf16 v[82:85], v[162:165], v[208:211], v[82:85]
	v_mfma_f32_16x16x32_bf16 v[82:85], v[158:161], v[182:185], v[82:85]
	v_mfma_f32_16x16x32_bf16 v[66:69], v[158:161], v[214:217], v[66:69]
	v_mfma_f32_16x16x32_bf16 v[66:69], v[162:165], v[218:221], v[66:69]
	v_mfma_f32_16x16x32_bf16 v[70:73], v[154:157], v[218:221], v[70:73]
	v_mfma_f32_16x16x32_bf16 v[70:73], v[150:153], v[214:217], v[70:73]
	v_mfma_f32_16x16x32_bf16 v[74:77], v[142:145], v[214:217], v[74:77]
	v_mfma_f32_16x16x32_bf16 v[74:77], v[146:149], v[218:221], v[74:77]
	v_mfma_f32_16x16x32_bf16 v[78:81], v[138:141], v[218:221], v[78:81]
	v_mfma_f32_16x16x32_bf16 v[78:81], v[134:137], v[214:217], v[78:81]
	s_barrier
	s_add_i32 s38, s63, s2
	s_add_u32 s36, s36, 0x80
	s_addc_u32 s37, s37, 0
	s_mov_b32 m0, s38
	ds_read_b128 v[166:169], v206 offset:49152
	ds_read_b128 v[170:173], v206 offset:50176
	ds_read_b128 v[174:177], v206 offset:51200
	ds_read_b128 v[178:181], v206 offset:52224
	ds_read_b128 v[182:185], v206 offset:53248
	ds_read_b128 v[208:211], v206 offset:54272
	ds_read_b128 v[214:217], v206 offset:55296
	ds_read_b128 v[218:221], v206 offset:56320
	global_load_lds_dwordx4 v188, s[36:37]
	s_add_i32 m0, s38, 0x2000
	s_add_i32 s38, s64, s2
	global_load_lds_dwordx4 v192, s[36:37]
	s_add_u32 s36, s36, 0x68000
	s_addc_u32 s37, s37, 0
	s_mov_b32 m0, s38
	s_nop 0
	global_load_lds_dwordx4 v188, s[36:37]
	s_add_i32 m0, s38, 0x2000
	s_nop 0
	global_load_lds_dwordx4 v192, s[36:37]
	s_mov_b32 m0, s50
	s_nop 0
	global_load_lds_dwordx4 v186, s[34:35]
	s_mov_b32 m0, s51
	s_nop 0
	global_load_lds_dwordx4 v190, s[34:35]
	s_waitcnt vmcnt(8)
	s_waitcnt lgkmcnt(0)
	s_barrier
	s_waitcnt lgkmcnt(0)
	v_mfma_f32_16x16x32_bf16 v[62:65], v[134:137], v[166:169], v[62:65]
	v_mfma_f32_16x16x32_bf16 v[62:65], v[138:141], v[170:173], v[62:65]
	v_mfma_f32_16x16x32_bf16 v[58:61], v[146:149], v[170:173], v[58:61]
	v_mfma_f32_16x16x32_bf16 v[58:61], v[142:145], v[166:169], v[58:61]
	v_mfma_f32_16x16x32_bf16 v[54:57], v[150:153], v[166:169], v[54:57]
	v_mfma_f32_16x16x32_bf16 v[54:57], v[154:157], v[170:173], v[54:57]
	v_mfma_f32_16x16x32_bf16 v[50:53], v[162:165], v[170:173], v[50:53]
	v_mfma_f32_16x16x32_bf16 v[50:53], v[158:161], v[166:169], v[50:53]
	v_mfma_f32_16x16x32_bf16 v[34:37], v[158:161], v[174:177], v[34:37]
	v_mfma_f32_16x16x32_bf16 v[34:37], v[162:165], v[178:181], v[34:37]
	v_mfma_f32_16x16x32_bf16 v[38:41], v[154:157], v[178:181], v[38:41]
	v_mfma_f32_16x16x32_bf16 v[38:41], v[150:153], v[174:177], v[38:41]
	v_mfma_f32_16x16x32_bf16 v[42:45], v[142:145], v[174:177], v[42:45]
	v_mfma_f32_16x16x32_bf16 v[42:45], v[146:149], v[178:181], v[42:45]
	v_mfma_f32_16x16x32_bf16 v[46:49], v[138:141], v[178:181], v[46:49]
	v_mfma_f32_16x16x32_bf16 v[46:49], v[134:137], v[174:177], v[46:49]
	v_mfma_f32_16x16x32_bf16 v[30:33], v[134:137], v[182:185], v[30:33]
	v_mfma_f32_16x16x32_bf16 v[30:33], v[138:141], v[208:211], v[30:33]
	v_mfma_f32_16x16x32_bf16 v[26:29], v[146:149], v[208:211], v[26:29]
	v_mfma_f32_16x16x32_bf16 v[26:29], v[142:145], v[182:185], v[26:29]
	v_mfma_f32_16x16x32_bf16 v[22:25], v[150:153], v[182:185], v[22:25]
	v_mfma_f32_16x16x32_bf16 v[22:25], v[154:157], v[208:211], v[22:25]
	v_mfma_f32_16x16x32_bf16 v[18:21], v[162:165], v[208:211], v[18:21]
	v_mfma_f32_16x16x32_bf16 v[18:21], v[158:161], v[182:185], v[18:21]
	v_mfma_f32_16x16x32_bf16 v[2:5], v[158:161], v[214:217], v[2:5]
	v_mfma_f32_16x16x32_bf16 v[2:5], v[162:165], v[218:221], v[2:5]
	v_mfma_f32_16x16x32_bf16 v[6:9], v[154:157], v[218:221], v[6:9]
	v_mfma_f32_16x16x32_bf16 v[6:9], v[150:153], v[214:217], v[6:9]
	v_mfma_f32_16x16x32_bf16 v[10:13], v[142:145], v[214:217], v[10:13]
	v_mfma_f32_16x16x32_bf16 v[10:13], v[146:149], v[218:221], v[10:13]
	v_mfma_f32_16x16x32_bf16 v[14:17], v[138:141], v[218:221], v[14:17]
	v_mfma_f32_16x16x32_bf16 v[14:17], v[134:137], v[214:217], v[14:17]
	s_barrier
	s_add_i32 s62, s62, 2
	s_add_u32 s30, s30, 0x100
	s_addc_u32 s31, s31, 0
	s_cmp_gt_u32 s62, 21
	s_cbranch_scc0 .LBB0_434
	s_and_b64 vcc, exec, s[14:15]
	s_cbranch_vccz .LBB0_437
	s_barrier

.LBB0_519:
	s_add_i32 s39, s56, 0xfffe8000
	s_and_b32 s38, s36, 0x100
	s_and_b32 s39, s39, 0x3e0000
	s_or_b32 s38, s38, s39
	s_add_u32 s57, s34, s38
	s_addc_u32 s59, s35, 0
	s_add_u32 s38, s36, 0x100
	s_addc_u32 s39, s37, 0
	s_add_i32 s41, s56, 0xffff8000
	s_and_b32 s40, s38, 0x100
	s_and_b32 s41, s41, 0x7e0000
	s_or_b32 s40, s41, s40
	s_add_u32 s40, s34, s40
	s_addc_u32 s41, s35, 0
	s_add_u32 s58, s53, s36
	s_addc_u32 s37, s54, s37
	s_add_i32 s42, s36, 0x180
	s_and_b32 s42, s42, 0x180
	s_and_b32 s43, s56, 0x7e0000
	s_or_b32 s42, s43, s42
	s_add_u32 s60, s34, s42
	s_addc_u32 s61, s35, 0
	s_cmpk_eq_i32 s36, 0x3f00
	s_cselect_b32 s43, s1, s41
	s_cselect_b32 s42, s21, s40
	s_cselect_b32 s41, s23, s37
	s_cselect_b32 s40, s22, s58
	s_cselect_b32 s37, s52, s61
	s_cselect_b32 s36, s31, s60
	s_add_i32 s60, 0, 0x10000
	v_add_u32_e32 v1, s60, v199
	ds_read_b128 v[130:133], v1
	ds_read_b128 v[134:137], v1 offset:1024
	ds_read_b128 v[138:141], v1 offset:2048
	ds_read_b128 v[142:145], v1 offset:3072
	ds_read_b128 v[146:149], v201
	ds_read_b128 v[150:153], v201 offset:1024
	ds_read_b128 v[154:157], v201 offset:2048
	ds_read_b128 v[158:161], v201 offset:3072
	s_add_u32 s58, s57, 0x10080
	s_addc_u32 s59, s59, 0
	s_add_i32 m0, s3, 0xc000
	ds_read_b128 v[162:165], v202
	ds_read_b128 v[166:169], v202 offset:1024
	ds_read_b128 v[170:173], v202 offset:2048
	ds_read_b128 v[174:177], v202 offset:3072
	ds_read_b128 v[186:189], v202 offset:4096
	ds_read_b128 v[190:193], v202 offset:5120
	ds_read_b128 v[194:197], v202 offset:6144
	ds_read_b128 v[204:207], v202 offset:7168
	global_load_lds_dwordx4 v178, s[58:59]
	s_add_i32 m0, s3, 0xe000
	s_nop 0
	global_load_lds_dwordx4 v182, s[58:59]
	s_waitcnt vmcnt(8)
	s_waitcnt lgkmcnt(0)
	s_barrier
	s_waitcnt lgkmcnt(0)
	v_mfma_f32_16x16x32_bf16 v[126:129], v[130:133], v[162:165], v[126:129]
	v_mfma_f32_16x16x32_bf16 v[126:129], v[134:137], v[166:169], v[126:129]
	v_mfma_f32_16x16x32_bf16 v[122:125], v[142:145], v[166:169], v[122:125]
	v_mfma_f32_16x16x32_bf16 v[122:125], v[138:141], v[162:165], v[122:125]
	v_mfma_f32_16x16x32_bf16 v[118:121], v[146:149], v[162:165], v[118:121]
	v_mfma_f32_16x16x32_bf16 v[118:121], v[150:153], v[166:169], v[118:121]
	v_mfma_f32_16x16x32_bf16 v[114:117], v[158:161], v[166:169], v[114:117]
	v_mfma_f32_16x16x32_bf16 v[114:117], v[154:157], v[162:165], v[114:117]
	v_mfma_f32_16x16x32_bf16 v[98:101], v[154:157], v[170:173], v[98:101]
	v_mfma_f32_16x16x32_bf16 v[98:101], v[158:161], v[174:177], v[98:101]
	v_mfma_f32_16x16x32_bf16 v[102:105], v[150:153], v[174:177], v[102:105]
	v_mfma_f32_16x16x32_bf16 v[102:105], v[146:149], v[170:173], v[102:105]
	v_mfma_f32_16x16x32_bf16 v[106:109], v[138:141], v[170:173], v[106:109]
	v_mfma_f32_16x16x32_bf16 v[106:109], v[142:145], v[174:177], v[106:109]
	v_mfma_f32_16x16x32_bf16 v[110:113], v[134:137], v[174:177], v[110:113]
	v_mfma_f32_16x16x32_bf16 v[110:113], v[130:133], v[170:173], v[110:113]
	v_mfma_f32_16x16x32_bf16 v[94:97], v[130:133], v[186:189], v[94:97]
	v_mfma_f32_16x16x32_bf16 v[94:97], v[134:137], v[190:193], v[94:97]
	v_mfma_f32_16x16x32_bf16 v[90:93], v[142:145], v[190:193], v[90:93]
	v_mfma_f32_16x16x32_bf16 v[90:93], v[138:141], v[186:189], v[90:93]
	v_mfma_f32_16x16x32_bf16 v[86:89], v[146:149], v[186:189], v[86:89]
	v_mfma_f32_16x16x32_bf16 v[86:89], v[150:153], v[190:193], v[86:89]
	v_mfma_f32_16x16x32_bf16 v[82:85], v[158:161], v[190:193], v[82:85]
	v_mfma_f32_16x16x32_bf16 v[82:85], v[154:157], v[186:189], v[82:85]
	v_mfma_f32_16x16x32_bf16 v[66:69], v[154:157], v[194:197], v[66:69]
	v_mfma_f32_16x16x32_bf16 v[66:69], v[158:161], v[204:207], v[66:69]
	v_mfma_f32_16x16x32_bf16 v[70:73], v[150:153], v[204:207], v[70:73]
	v_mfma_f32_16x16x32_bf16 v[70:73], v[146:149], v[194:197], v[70:73]
	v_mfma_f32_16x16x32_bf16 v[74:77], v[138:141], v[194:197], v[74:77]
	v_mfma_f32_16x16x32_bf16 v[74:77], v[142:145], v[204:207], v[74:77]
	v_mfma_f32_16x16x32_bf16 v[78:81], v[134:137], v[204:207], v[78:81]
	v_mfma_f32_16x16x32_bf16 v[78:81], v[130:133], v[194:197], v[78:81]
	s_barrier
	s_add_i32 s57, s60, s2
	v_lshl_add_u64 v[208:209], s[40:41], 0, v[180:181]
	s_mov_b32 m0, s57
	ds_read_b128 v[162:165], v202 offset:16384
	ds_read_b128 v[166:169], v202 offset:17408
	ds_read_b128 v[170:173], v202 offset:18432
	ds_read_b128 v[174:177], v202 offset:19456
	ds_read_b128 v[186:189], v202 offset:20480
	ds_read_b128 v[190:193], v202 offset:21504
	ds_read_b128 v[194:197], v202 offset:22528
	ds_read_b128 v[204:207], v202 offset:23552
	global_load_lds_dwordx4 v[208:209], off
	s_add_i32 m0, s57, 0x2000
	s_add_u32 s58, s40, 0x208000
	v_lshl_add_u64 v[210:211], s[40:41], 0, v[184:185]
	s_addc_u32 s59, s41, 0
	s_add_i32 s57, s49, s2
	global_load_lds_dwordx4 v[210:211], off
	s_mov_b32 m0, s57
	s_nop 0
	global_load_lds_dwordx4 v180, s[58:59]
	s_add_i32 m0, s57, 0x2000
	s_nop 0
	global_load_lds_dwordx4 v184, s[58:59]
	s_mov_b32 m0, s3
	s_nop 0
	global_load_lds_dwordx4 v178, s[42:43]
	s_mov_b32 m0, s33
	s_nop 0
	global_load_lds_dwordx4 v182, s[42:43]
	s_waitcnt vmcnt(8)
	s_waitcnt lgkmcnt(0)
	s_barrier
	s_waitcnt lgkmcnt(0)
	v_mfma_f32_16x16x32_bf16 v[62:65], v[130:133], v[162:165], v[62:65]
	v_mfma_f32_16x16x32_bf16 v[62:65], v[134:137], v[166:169], v[62:65]
	v_mfma_f32_16x16x32_bf16 v[58:61], v[142:145], v[166:169], v[58:61]
	v_mfma_f32_16x16x32_bf16 v[58:61], v[138:141], v[162:165], v[58:61]
	v_mfma_f32_16x16x32_bf16 v[54:57], v[146:149], v[162:165], v[54:57]
	v_mfma_f32_16x16x32_bf16 v[54:57], v[150:153], v[166:169], v[54:57]
	v_mfma_f32_16x16x32_bf16 v[50:53], v[158:161], v[166:169], v[50:53]
	v_mfma_f32_16x16x32_bf16 v[50:53], v[154:157], v[162:165], v[50:53]
	v_mfma_f32_16x16x32_bf16 v[34:37], v[154:157], v[170:173], v[34:37]
	v_mfma_f32_16x16x32_bf16 v[34:37], v[158:161], v[174:177], v[34:37]
	v_mfma_f32_16x16x32_bf16 v[38:41], v[150:153], v[174:177], v[38:41]
	v_mfma_f32_16x16x32_bf16 v[38:41], v[146:149], v[170:173], v[38:41]
	v_mfma_f32_16x16x32_bf16 v[42:45], v[138:141], v[170:173], v[42:45]
	v_mfma_f32_16x16x32_bf16 v[42:45], v[142:145], v[174:177], v[42:45]
	v_mfma_f32_16x16x32_bf16 v[46:49], v[134:137], v[174:177], v[46:49]
	v_mfma_f32_16x16x32_bf16 v[46:49], v[130:133], v[170:173], v[46:49]
	v_mfma_f32_16x16x32_bf16 v[30:33], v[130:133], v[186:189], v[30:33]
	v_mfma_f32_16x16x32_bf16 v[30:33], v[134:137], v[190:193], v[30:33]
	v_mfma_f32_16x16x32_bf16 v[26:29], v[142:145], v[190:193], v[26:29]
	v_mfma_f32_16x16x32_bf16 v[26:29], v[138:141], v[186:189], v[26:29]
	v_mfma_f32_16x16x32_bf16 v[22:25], v[146:149], v[186:189], v[22:25]
	v_mfma_f32_16x16x32_bf16 v[22:25], v[150:153], v[190:193], v[22:25]
	v_mfma_f32_16x16x32_bf16 v[18:21], v[158:161], v[190:193], v[18:21]
	v_mfma_f32_16x16x32_bf16 v[18:21], v[154:157], v[186:189], v[18:21]
	v_mfma_f32_16x16x32_bf16 v[2:5], v[154:157], v[194:197], v[2:5]
	v_mfma_f32_16x16x32_bf16 v[2:5], v[158:161], v[204:207], v[2:5]
	v_mfma_f32_16x16x32_bf16 v[6:9], v[150:153], v[204:207], v[6:9]
	v_mfma_f32_16x16x32_bf16 v[6:9], v[146:149], v[194:197], v[6:9]
	v_mfma_f32_16x16x32_bf16 v[10:13], v[138:141], v[194:197], v[10:13]
	v_mfma_f32_16x16x32_bf16 v[10:13], v[142:145], v[204:207], v[10:13]
	v_mfma_f32_16x16x32_bf16 v[14:17], v[134:137], v[204:207], v[14:17]
	v_mfma_f32_16x16x32_bf16 v[14:17], v[130:133], v[194:197], v[14:17]
	s_barrier
	s_add_i32 s57, 0, 0x18000
	v_add_u32_e32 v1, s57, v199
	s_add_i32 s58, 0, 0x1c000
	ds_read_b128 v[130:133], v1
	ds_read_b128 v[134:137], v1 offset:1024
	ds_read_b128 v[138:141], v1 offset:2048
	ds_read_b128 v[142:145], v1 offset:3072
	v_add_u32_e32 v1, s58, v199
	ds_read_b128 v[146:149], v1
	ds_read_b128 v[150:153], v1 offset:1024
	ds_read_b128 v[154:157], v1 offset:2048
	ds_read_b128 v[158:161], v1 offset:3072
	s_add_u32 s42, s42, 0x10000
	s_addc_u32 s43, s43, 0
	s_mov_b32 m0, s44
	ds_read_b128 v[162:165], v202 offset:32768
	ds_read_b128 v[166:169], v202 offset:33792
	ds_read_b128 v[170:173], v202 offset:34816
	ds_read_b128 v[174:177], v202 offset:35840
	ds_read_b128 v[186:189], v202 offset:36864
	ds_read_b128 v[190:193], v202 offset:37888
	ds_read_b128 v[194:197], v202 offset:38912
	ds_read_b128 v[204:207], v202 offset:39936
	global_load_lds_dwordx4 v178, s[42:43]
	v_lshl_add_u64 v[214:215], s[42:43], 0, v[182:183]
	s_mov_b32 m0, s45
	s_nop 0
	global_load_lds_dwordx4 v[214:215], off
	s_waitcnt vmcnt(8)
	s_waitcnt lgkmcnt(0)
	s_barrier
	s_waitcnt lgkmcnt(0)
	v_mfma_f32_16x16x32_bf16 v[126:129], v[130:133], v[162:165], v[126:129]
	v_mfma_f32_16x16x32_bf16 v[126:129], v[134:137], v[166:169], v[126:129]
	v_mfma_f32_16x16x32_bf16 v[122:125], v[142:145], v[166:169], v[122:125]
	v_mfma_f32_16x16x32_bf16 v[122:125], v[138:141], v[162:165], v[122:125]
	v_mfma_f32_16x16x32_bf16 v[118:121], v[146:149], v[162:165], v[118:121]
	v_mfma_f32_16x16x32_bf16 v[118:121], v[150:153], v[166:169], v[118:121]
	v_mfma_f32_16x16x32_bf16 v[114:117], v[158:161], v[166:169], v[114:117]
	v_mfma_f32_16x16x32_bf16 v[114:117], v[154:157], v[162:165], v[114:117]
	v_mfma_f32_16x16x32_bf16 v[98:101], v[154:157], v[170:173], v[98:101]
	v_mfma_f32_16x16x32_bf16 v[98:101], v[158:161], v[174:177], v[98:101]
	v_mfma_f32_16x16x32_bf16 v[102:105], v[150:153], v[174:177], v[102:105]
	v_mfma_f32_16x16x32_bf16 v[102:105], v[146:149], v[170:173], v[102:105]
	v_mfma_f32_16x16x32_bf16 v[106:109], v[138:141], v[170:173], v[106:109]
	v_mfma_f32_16x16x32_bf16 v[106:109], v[142:145], v[174:177], v[106:109]
	v_mfma_f32_16x16x32_bf16 v[110:113], v[134:137], v[174:177], v[110:113]
	v_mfma_f32_16x16x32_bf16 v[110:113], v[130:133], v[170:173], v[110:113]
	v_mfma_f32_16x16x32_bf16 v[94:97], v[130:133], v[186:189], v[94:97]
	v_mfma_f32_16x16x32_bf16 v[94:97], v[134:137], v[190:193], v[94:97]
	v_mfma_f32_16x16x32_bf16 v[90:93], v[142:145], v[190:193], v[90:93]
	v_mfma_f32_16x16x32_bf16 v[90:93], v[138:141], v[186:189], v[90:93]
	v_mfma_f32_16x16x32_bf16 v[86:89], v[146:149], v[186:189], v[86:89]
	v_mfma_f32_16x16x32_bf16 v[86:89], v[150:153], v[190:193], v[86:89]
	v_mfma_f32_16x16x32_bf16 v[82:85], v[158:161], v[190:193], v[82:85]
	v_mfma_f32_16x16x32_bf16 v[82:85], v[154:157], v[186:189], v[82:85]
	v_mfma_f32_16x16x32_bf16 v[66:69], v[154:157], v[194:197], v[66:69]
	v_mfma_f32_16x16x32_bf16 v[66:69], v[158:161], v[204:207], v[66:69]
	v_mfma_f32_16x16x32_bf16 v[70:73], v[150:153], v[204:207], v[70:73]
	v_mfma_f32_16x16x32_bf16 v[70:73], v[146:149], v[194:197], v[70:73]
	v_mfma_f32_16x16x32_bf16 v[74:77], v[138:141], v[194:197], v[74:77]
	v_mfma_f32_16x16x32_bf16 v[74:77], v[142:145], v[204:207], v[74:77]
	v_mfma_f32_16x16x32_bf16 v[78:81], v[134:137], v[204:207], v[78:81]
	v_mfma_f32_16x16x32_bf16 v[78:81], v[130:133], v[194:197], v[78:81]
	s_barrier
	s_add_i32 s42, s57, s2
	v_lshl_add_u64 v[208:209], v[208:209], 0, s[16:17]
	s_mov_b32 m0, s42
	ds_read_b128 v[162:165], v202 offset:49152
	ds_read_b128 v[166:169], v202 offset:50176
	ds_read_b128 v[170:173], v202 offset:51200
	ds_read_b128 v[174:177], v202 offset:52224
	ds_read_b128 v[186:189], v202 offset:53248
	ds_read_b128 v[190:193], v202 offset:54272
	ds_read_b128 v[194:197], v202 offset:55296
	ds_read_b128 v[204:207], v202 offset:56320
	global_load_lds_dwordx4 v[208:209], off
	s_add_i32 m0, s42, 0x2000
	s_add_u32 s40, s40, 0x208080
	v_lshl_add_u64 v[208:209], v[210:211], 0, s[16:17]
	s_addc_u32 s41, s41, 0
	s_add_i32 s42, s58, s2
	global_load_lds_dwordx4 v[208:209], off
	s_mov_b32 m0, s42
	s_nop 0
	global_load_lds_dwordx4 v180, s[40:41]
	s_add_i32 m0, s42, 0x2000
	s_nop 0
	global_load_lds_dwordx4 v184, s[40:41]
	s_mov_b32 m0, s47
	s_nop 0
	global_load_lds_dwordx4 v178, s[36:37]
	v_lshl_add_u64 v[208:209], s[36:37], 0, v[182:183]
	s_mov_b32 m0, s48
	s_nop 0
	global_load_lds_dwordx4 v[208:209], off
	s_waitcnt vmcnt(8)
	s_waitcnt lgkmcnt(0)
	s_barrier
	s_waitcnt lgkmcnt(0)
	v_mfma_f32_16x16x32_bf16 v[62:65], v[130:133], v[162:165], v[62:65]
	v_mfma_f32_16x16x32_bf16 v[62:65], v[134:137], v[166:169], v[62:65]
	v_mfma_f32_16x16x32_bf16 v[58:61], v[142:145], v[166:169], v[58:61]
	v_mfma_f32_16x16x32_bf16 v[58:61], v[138:141], v[162:165], v[58:61]
	v_mfma_f32_16x16x32_bf16 v[54:57], v[146:149], v[162:165], v[54:57]
	v_mfma_f32_16x16x32_bf16 v[54:57], v[150:153], v[166:169], v[54:57]
	v_mfma_f32_16x16x32_bf16 v[50:53], v[158:161], v[166:169], v[50:53]
	v_mfma_f32_16x16x32_bf16 v[50:53], v[154:157], v[162:165], v[50:53]
	v_mfma_f32_16x16x32_bf16 v[34:37], v[154:157], v[170:173], v[34:37]
	v_mfma_f32_16x16x32_bf16 v[34:37], v[158:161], v[174:177], v[34:37]
	v_mfma_f32_16x16x32_bf16 v[38:41], v[150:153], v[174:177], v[38:41]
	v_mfma_f32_16x16x32_bf16 v[38:41], v[146:149], v[170:173], v[38:41]
	v_mfma_f32_16x16x32_bf16 v[42:45], v[138:141], v[170:173], v[42:45]
	v_mfma_f32_16x16x32_bf16 v[42:45], v[142:145], v[174:177], v[42:45]
	v_mfma_f32_16x16x32_bf16 v[46:49], v[134:137], v[174:177], v[46:49]
	v_mfma_f32_16x16x32_bf16 v[46:49], v[130:133], v[170:173], v[46:49]
	v_mfma_f32_16x16x32_bf16 v[30:33], v[130:133], v[186:189], v[30:33]
	v_mfma_f32_16x16x32_bf16 v[30:33], v[134:137], v[190:193], v[30:33]
	v_mfma_f32_16x16x32_bf16 v[26:29], v[142:145], v[190:193], v[26:29]
	v_mfma_f32_16x16x32_bf16 v[26:29], v[138:141], v[186:189], v[26:29]
	v_mfma_f32_16x16x32_bf16 v[22:25], v[146:149], v[186:189], v[22:25]
	v_mfma_f32_16x16x32_bf16 v[22:25], v[150:153], v[190:193], v[22:25]
	v_mfma_f32_16x16x32_bf16 v[18:21], v[158:161], v[190:193], v[18:21]
	v_mfma_f32_16x16x32_bf16 v[18:21], v[154:157], v[186:189], v[18:21]
	v_mfma_f32_16x16x32_bf16 v[2:5], v[154:157], v[194:197], v[2:5]
	v_mfma_f32_16x16x32_bf16 v[2:5], v[158:161], v[204:207], v[2:5]
	v_mfma_f32_16x16x32_bf16 v[6:9], v[150:153], v[204:207], v[6:9]
	v_mfma_f32_16x16x32_bf16 v[6:9], v[146:149], v[194:197], v[6:9]
	v_mfma_f32_16x16x32_bf16 v[10:13], v[138:141], v[194:197], v[10:13]
	v_mfma_f32_16x16x32_bf16 v[10:13], v[142:145], v[204:207], v[10:13]
	v_mfma_f32_16x16x32_bf16 v[14:17], v[134:137], v[204:207], v[14:17]
	v_mfma_f32_16x16x32_bf16 v[14:17], v[130:133], v[194:197], v[14:17]
	s_barrier
	s_add_i32 s55, s55, 2
	s_add_i32 s56, s56, 0x10000
	s_cmpk_gt_u32 s55, 0x7d
	s_mov_b64 s[36:37], s[38:39]
	s_cbranch_scc0 .LBB0_519
	s_and_b64 vcc, exec, s[18:19]
	s_cbranch_vccz .LBB0_522
	s_barrier

.LBB0_612:
	ds_read_b128 v[166:169], v152
	ds_read_b128 v[170:173], v152 offset:1024
	ds_read_b128 v[174:177], v152 offset:2048
	ds_read_b128 v[178:181], v152 offset:3072
	ds_read_b128 v[182:185], v153
	ds_read_b128 v[186:189], v153 offset:1024
	ds_read_b128 v[190:193], v153 offset:2048
	ds_read_b128 v[194:197], v153 offset:3072
	s_add_u32 s26, s4, s22
	s_addc_u32 s27, s5, s23
	s_add_u32 s30, s26, 0x100
	s_addc_u32 s31, s27, 0
	s_add_u32 s28, s52, s22
	s_addc_u32 s29, s53, s23
	s_add_u32 s26, s26, 0x180
	s_addc_u32 s27, s27, 0
	s_cmpk_eq_i32 s22, 0x1f00
	s_cselect_b32 s27, s51, s27
	s_cselect_b32 s26, s50, s26
	s_cselect_b32 s29, s21, s29
	s_cselect_b32 s28, s20, s28
	s_cselect_b32 s31, s19, s31
	s_cselect_b32 s30, s18, s30
	s_mov_b32 m0, s37
	v_lshl_add_u64 v[210:211], v[148:149], 0, s[22:23]
	ds_read_b128 v[198:201], v154
	ds_read_b128 v[202:205], v154 offset:1024
	ds_read_b128 v[206:209], v154 offset:2048
	ds_read_b128 v[214:217], v154 offset:3072
	ds_read_b128 v[218:221], v154 offset:4096
	ds_read_b128 v[222:225], v154 offset:5120
	ds_read_b128 v[226:229], v154 offset:6144
	ds_read_b128 v[230:233], v154 offset:7168
	global_load_lds_dwordx4 v[210:211], off
	v_lshl_add_u64 v[210:211], v[150:151], 0, s[22:23]
	s_mov_b32 m0, s38
	s_nop 0
	global_load_lds_dwordx4 v[210:211], off
	s_waitcnt vmcnt(8)
	s_waitcnt lgkmcnt(0)
	s_barrier
	s_waitcnt lgkmcnt(0)
	v_mfma_f32_16x16x32_bf16 v[126:129], v[166:169], v[198:201], v[126:129]
	v_mfma_f32_16x16x32_bf16 v[126:129], v[170:173], v[202:205], v[126:129]
	v_mfma_f32_16x16x32_bf16 v[122:125], v[178:181], v[202:205], v[122:125]
	v_mfma_f32_16x16x32_bf16 v[122:125], v[174:177], v[198:201], v[122:125]
	v_mfma_f32_16x16x32_bf16 v[118:121], v[182:185], v[198:201], v[118:121]
	v_mfma_f32_16x16x32_bf16 v[118:121], v[186:189], v[202:205], v[118:121]
	v_mfma_f32_16x16x32_bf16 v[114:117], v[194:197], v[202:205], v[114:117]
	v_mfma_f32_16x16x32_bf16 v[114:117], v[190:193], v[198:201], v[114:117]
	v_mfma_f32_16x16x32_bf16 v[98:101], v[190:193], v[206:209], v[98:101]
	v_mfma_f32_16x16x32_bf16 v[98:101], v[194:197], v[214:217], v[98:101]
	v_mfma_f32_16x16x32_bf16 v[102:105], v[186:189], v[214:217], v[102:105]
	v_mfma_f32_16x16x32_bf16 v[102:105], v[182:185], v[206:209], v[102:105]
	v_mfma_f32_16x16x32_bf16 v[106:109], v[174:177], v[206:209], v[106:109]
	v_mfma_f32_16x16x32_bf16 v[106:109], v[178:181], v[214:217], v[106:109]
	v_mfma_f32_16x16x32_bf16 v[110:113], v[170:173], v[214:217], v[110:113]
	v_mfma_f32_16x16x32_bf16 v[110:113], v[166:169], v[206:209], v[110:113]
	v_mfma_f32_16x16x32_bf16 v[94:97], v[166:169], v[218:221], v[94:97]
	v_mfma_f32_16x16x32_bf16 v[94:97], v[170:173], v[222:225], v[94:97]
	v_mfma_f32_16x16x32_bf16 v[90:93], v[178:181], v[222:225], v[90:93]
	v_mfma_f32_16x16x32_bf16 v[90:93], v[174:177], v[218:221], v[90:93]
	v_mfma_f32_16x16x32_bf16 v[86:89], v[182:185], v[218:221], v[86:89]
	v_mfma_f32_16x16x32_bf16 v[86:89], v[186:189], v[222:225], v[86:89]
	v_mfma_f32_16x16x32_bf16 v[82:85], v[194:197], v[222:225], v[82:85]
	v_mfma_f32_16x16x32_bf16 v[82:85], v[190:193], v[218:221], v[82:85]
	v_mfma_f32_16x16x32_bf16 v[66:69], v[190:193], v[226:229], v[66:69]
	v_mfma_f32_16x16x32_bf16 v[66:69], v[194:197], v[230:233], v[66:69]
	v_mfma_f32_16x16x32_bf16 v[70:73], v[186:189], v[230:233], v[70:73]
	v_mfma_f32_16x16x32_bf16 v[70:73], v[182:185], v[226:229], v[70:73]
	v_mfma_f32_16x16x32_bf16 v[74:77], v[174:177], v[226:229], v[74:77]
	v_mfma_f32_16x16x32_bf16 v[74:77], v[178:181], v[230:233], v[74:77]
	v_mfma_f32_16x16x32_bf16 v[78:81], v[170:173], v[230:233], v[78:81]
	v_mfma_f32_16x16x32_bf16 v[78:81], v[166:169], v[226:229], v[78:81]
	s_barrier
	s_mov_b32 m0, s39
	s_add_u32 s56, s28, 0x108000
	ds_read_b128 v[198:201], v154 offset:16384
	ds_read_b128 v[202:205], v154 offset:17408
	ds_read_b128 v[206:209], v154 offset:18432
	ds_read_b128 v[214:217], v154 offset:19456
	ds_read_b128 v[218:221], v154 offset:20480
	ds_read_b128 v[222:225], v154 offset:21504
	ds_read_b128 v[226:229], v154 offset:22528
	ds_read_b128 v[230:233], v154 offset:23552
	global_load_lds_dwordx4 v132, s[28:29]
	s_mov_b32 m0, s40
	s_addc_u32 s57, s29, 0
	global_load_lds_dwordx4 v136, s[28:29]
	s_mov_b32 m0, s41
	s_nop 0
	global_load_lds_dwordx4 v132, s[56:57]
	s_mov_b32 m0, s42
	s_nop 0
	global_load_lds_dwordx4 v136, s[56:57]
	s_mov_b32 m0, s2
	s_nop 0
	global_load_lds_dwordx4 v130, s[30:31]
	s_mov_b32 m0, s3
	s_nop 0
	global_load_lds_dwordx4 v134, s[30:31]
	s_waitcnt vmcnt(8)
	s_waitcnt lgkmcnt(0)
	s_barrier
	s_waitcnt lgkmcnt(0)
	v_mfma_f32_16x16x32_bf16 v[62:65], v[166:169], v[198:201], v[62:65]
	v_mfma_f32_16x16x32_bf16 v[62:65], v[170:173], v[202:205], v[62:65]
	v_mfma_f32_16x16x32_bf16 v[58:61], v[178:181], v[202:205], v[58:61]
	v_mfma_f32_16x16x32_bf16 v[58:61], v[174:177], v[198:201], v[58:61]
	v_mfma_f32_16x16x32_bf16 v[54:57], v[182:185], v[198:201], v[54:57]
	v_mfma_f32_16x16x32_bf16 v[54:57], v[186:189], v[202:205], v[54:57]
	v_mfma_f32_16x16x32_bf16 v[50:53], v[194:197], v[202:205], v[50:53]
	v_mfma_f32_16x16x32_bf16 v[50:53], v[190:193], v[198:201], v[50:53]
	v_mfma_f32_16x16x32_bf16 v[34:37], v[190:193], v[206:209], v[34:37]
	v_mfma_f32_16x16x32_bf16 v[34:37], v[194:197], v[214:217], v[34:37]
	v_mfma_f32_16x16x32_bf16 v[38:41], v[186:189], v[214:217], v[38:41]
	v_mfma_f32_16x16x32_bf16 v[38:41], v[182:185], v[206:209], v[38:41]
	v_mfma_f32_16x16x32_bf16 v[42:45], v[174:177], v[206:209], v[42:45]
	v_mfma_f32_16x16x32_bf16 v[42:45], v[178:181], v[214:217], v[42:45]
	v_mfma_f32_16x16x32_bf16 v[46:49], v[170:173], v[214:217], v[46:49]
	v_mfma_f32_16x16x32_bf16 v[46:49], v[166:169], v[206:209], v[46:49]
	v_mfma_f32_16x16x32_bf16 v[30:33], v[166:169], v[218:221], v[30:33]
	v_mfma_f32_16x16x32_bf16 v[30:33], v[170:173], v[222:225], v[30:33]
	v_mfma_f32_16x16x32_bf16 v[26:29], v[178:181], v[222:225], v[26:29]
	v_mfma_f32_16x16x32_bf16 v[26:29], v[174:177], v[218:221], v[26:29]
	v_mfma_f32_16x16x32_bf16 v[22:25], v[182:185], v[218:221], v[22:25]
	v_mfma_f32_16x16x32_bf16 v[22:25], v[186:189], v[222:225], v[22:25]
	v_mfma_f32_16x16x32_bf16 v[18:21], v[194:197], v[222:225], v[18:21]
	v_mfma_f32_16x16x32_bf16 v[18:21], v[190:193], v[218:221], v[18:21]
	v_mfma_f32_16x16x32_bf16 v[2:5], v[190:193], v[226:229], v[2:5]
	v_mfma_f32_16x16x32_bf16 v[2:5], v[194:197], v[230:233], v[2:5]
	v_mfma_f32_16x16x32_bf16 v[6:9], v[186:189], v[230:233], v[6:9]
	v_mfma_f32_16x16x32_bf16 v[6:9], v[182:185], v[226:229], v[6:9]
	v_mfma_f32_16x16x32_bf16 v[10:13], v[174:177], v[226:229], v[10:13]
	v_mfma_f32_16x16x32_bf16 v[10:13], v[178:181], v[230:233], v[10:13]
	v_mfma_f32_16x16x32_bf16 v[14:17], v[170:173], v[230:233], v[14:17]
	v_mfma_f32_16x16x32_bf16 v[14:17], v[166:169], v[226:229], v[14:17]
	s_barrier
	ds_read_b128 v[166:169], v156
	ds_read_b128 v[170:173], v156 offset:1024
	ds_read_b128 v[174:177], v156 offset:2048
	ds_read_b128 v[178:181], v156 offset:3072
	ds_read_b128 v[182:185], v157
	ds_read_b128 v[186:189], v157 offset:1024
	ds_read_b128 v[190:193], v157 offset:2048
	ds_read_b128 v[194:197], v157 offset:3072
	s_add_u32 s30, s30, 0x108000
	s_addc_u32 s31, s31, 0
	s_mov_b32 m0, s33
	ds_read_b128 v[198:201], v154 offset:32768
	ds_read_b128 v[202:205], v154 offset:33792
	ds_read_b128 v[206:209], v154 offset:34816
	ds_read_b128 v[214:217], v154 offset:35840
	ds_read_b128 v[218:221], v154 offset:36864
	ds_read_b128 v[222:225], v154 offset:37888
	ds_read_b128 v[226:229], v154 offset:38912
	ds_read_b128 v[230:233], v154 offset:39936
	global_load_lds_dwordx4 v130, s[30:31]
	s_mov_b32 m0, s34
	s_nop 0
	global_load_lds_dwordx4 v134, s[30:31]
	s_waitcnt vmcnt(8)
	s_waitcnt lgkmcnt(0)
	s_barrier
	s_waitcnt lgkmcnt(0)
	v_mfma_f32_16x16x32_bf16 v[126:129], v[166:169], v[198:201], v[126:129]
	v_mfma_f32_16x16x32_bf16 v[126:129], v[170:173], v[202:205], v[126:129]
	v_mfma_f32_16x16x32_bf16 v[122:125], v[178:181], v[202:205], v[122:125]
	v_mfma_f32_16x16x32_bf16 v[122:125], v[174:177], v[198:201], v[122:125]
	v_mfma_f32_16x16x32_bf16 v[118:121], v[182:185], v[198:201], v[118:121]
	v_mfma_f32_16x16x32_bf16 v[118:121], v[186:189], v[202:205], v[118:121]
	v_mfma_f32_16x16x32_bf16 v[114:117], v[194:197], v[202:205], v[114:117]
	v_mfma_f32_16x16x32_bf16 v[114:117], v[190:193], v[198:201], v[114:117]
	v_mfma_f32_16x16x32_bf16 v[98:101], v[190:193], v[206:209], v[98:101]
	v_mfma_f32_16x16x32_bf16 v[98:101], v[194:197], v[214:217], v[98:101]
	v_mfma_f32_16x16x32_bf16 v[102:105], v[186:189], v[214:217], v[102:105]
	v_mfma_f32_16x16x32_bf16 v[102:105], v[182:185], v[206:209], v[102:105]
	v_mfma_f32_16x16x32_bf16 v[106:109], v[174:177], v[206:209], v[106:109]
	v_mfma_f32_16x16x32_bf16 v[106:109], v[178:181], v[214:217], v[106:109]
	v_mfma_f32_16x16x32_bf16 v[110:113], v[170:173], v[214:217], v[110:113]
	v_mfma_f32_16x16x32_bf16 v[110:113], v[166:169], v[206:209], v[110:113]
	v_mfma_f32_16x16x32_bf16 v[94:97], v[166:169], v[218:221], v[94:97]
	v_mfma_f32_16x16x32_bf16 v[94:97], v[170:173], v[222:225], v[94:97]
	v_mfma_f32_16x16x32_bf16 v[90:93], v[178:181], v[222:225], v[90:93]
	v_mfma_f32_16x16x32_bf16 v[90:93], v[174:177], v[218:221], v[90:93]
	v_mfma_f32_16x16x32_bf16 v[86:89], v[182:185], v[218:221], v[86:89]
	v_mfma_f32_16x16x32_bf16 v[86:89], v[186:189], v[222:225], v[86:89]
	v_mfma_f32_16x16x32_bf16 v[82:85], v[194:197], v[222:225], v[82:85]
	v_mfma_f32_16x16x32_bf16 v[82:85], v[190:193], v[218:221], v[82:85]
	v_mfma_f32_16x16x32_bf16 v[66:69], v[190:193], v[226:229], v[66:69]
	v_mfma_f32_16x16x32_bf16 v[66:69], v[194:197], v[230:233], v[66:69]
	v_mfma_f32_16x16x32_bf16 v[70:73], v[186:189], v[230:233], v[70:73]
	v_mfma_f32_16x16x32_bf16 v[70:73], v[182:185], v[226:229], v[70:73]
	v_mfma_f32_16x16x32_bf16 v[74:77], v[174:177], v[226:229], v[74:77]
	v_mfma_f32_16x16x32_bf16 v[74:77], v[178:181], v[230:233], v[74:77]
	v_mfma_f32_16x16x32_bf16 v[78:81], v[170:173], v[230:233], v[78:81]
	v_mfma_f32_16x16x32_bf16 v[78:81], v[166:169], v[226:229], v[78:81]
	s_barrier
	s_mov_b32 m0, s43
	s_add_u32 s28, s28, 0x80
	s_addc_u32 s29, s29, 0
	ds_read_b128 v[198:201], v154 offset:49152
	ds_read_b128 v[202:205], v154 offset:50176
	ds_read_b128 v[206:209], v154 offset:51200
	ds_read_b128 v[214:217], v154 offset:52224
	ds_read_b128 v[218:221], v154 offset:53248
	ds_read_b128 v[222:225], v154 offset:54272
	ds_read_b128 v[226:229], v154 offset:55296
	ds_read_b128 v[230:233], v154 offset:56320
	global_load_lds_dwordx4 v132, s[28:29]
	s_mov_b32 m0, s44
	s_nop 0
	global_load_lds_dwordx4 v136, s[28:29]
	s_add_u32 s28, s28, 0x108000
	s_addc_u32 s29, s29, 0
	s_mov_b32 m0, s45
	s_nop 0
	global_load_lds_dwordx4 v132, s[28:29]
	s_mov_b32 m0, s46
	s_nop 0
	global_load_lds_dwordx4 v136, s[28:29]
	s_mov_b32 m0, s35
	s_nop 0
	global_load_lds_dwordx4 v130, s[26:27]
	s_mov_b32 m0, s36
	s_nop 0
	global_load_lds_dwordx4 v134, s[26:27]
	s_waitcnt vmcnt(8)
	s_waitcnt lgkmcnt(0)
	s_barrier
	s_waitcnt lgkmcnt(0)
	v_mfma_f32_16x16x32_bf16 v[62:65], v[166:169], v[198:201], v[62:65]
	v_mfma_f32_16x16x32_bf16 v[62:65], v[170:173], v[202:205], v[62:65]
	v_mfma_f32_16x16x32_bf16 v[58:61], v[178:181], v[202:205], v[58:61]
	v_mfma_f32_16x16x32_bf16 v[58:61], v[174:177], v[198:201], v[58:61]
	v_mfma_f32_16x16x32_bf16 v[54:57], v[182:185], v[198:201], v[54:57]
	v_mfma_f32_16x16x32_bf16 v[54:57], v[186:189], v[202:205], v[54:57]
	v_mfma_f32_16x16x32_bf16 v[50:53], v[194:197], v[202:205], v[50:53]
	v_mfma_f32_16x16x32_bf16 v[50:53], v[190:193], v[198:201], v[50:53]
	v_mfma_f32_16x16x32_bf16 v[34:37], v[190:193], v[206:209], v[34:37]
	v_mfma_f32_16x16x32_bf16 v[34:37], v[194:197], v[214:217], v[34:37]
	v_mfma_f32_16x16x32_bf16 v[38:41], v[186:189], v[214:217], v[38:41]
	v_mfma_f32_16x16x32_bf16 v[38:41], v[182:185], v[206:209], v[38:41]
	v_mfma_f32_16x16x32_bf16 v[42:45], v[174:177], v[206:209], v[42:45]
	v_mfma_f32_16x16x32_bf16 v[42:45], v[178:181], v[214:217], v[42:45]
	v_mfma_f32_16x16x32_bf16 v[46:49], v[170:173], v[214:217], v[46:49]
	v_mfma_f32_16x16x32_bf16 v[46:49], v[166:169], v[206:209], v[46:49]
	v_mfma_f32_16x16x32_bf16 v[30:33], v[166:169], v[218:221], v[30:33]
	v_mfma_f32_16x16x32_bf16 v[30:33], v[170:173], v[222:225], v[30:33]
	v_mfma_f32_16x16x32_bf16 v[26:29], v[178:181], v[222:225], v[26:29]
	v_mfma_f32_16x16x32_bf16 v[26:29], v[174:177], v[218:221], v[26:29]
	v_mfma_f32_16x16x32_bf16 v[22:25], v[182:185], v[218:221], v[22:25]
	v_mfma_f32_16x16x32_bf16 v[22:25], v[186:189], v[222:225], v[22:25]
	v_mfma_f32_16x16x32_bf16 v[18:21], v[194:197], v[222:225], v[18:21]
	v_mfma_f32_16x16x32_bf16 v[18:21], v[190:193], v[218:221], v[18:21]
	v_mfma_f32_16x16x32_bf16 v[2:5], v[190:193], v[226:229], v[2:5]
	v_mfma_f32_16x16x32_bf16 v[2:5], v[194:197], v[230:233], v[2:5]
	v_mfma_f32_16x16x32_bf16 v[6:9], v[186:189], v[230:233], v[6:9]
	v_mfma_f32_16x16x32_bf16 v[6:9], v[182:185], v[226:229], v[6:9]
	v_mfma_f32_16x16x32_bf16 v[10:13], v[174:177], v[226:229], v[10:13]
	v_mfma_f32_16x16x32_bf16 v[10:13], v[178:181], v[230:233], v[10:13]
	v_mfma_f32_16x16x32_bf16 v[14:17], v[170:173], v[230:233], v[14:17]
	v_mfma_f32_16x16x32_bf16 v[14:17], v[166:169], v[226:229], v[14:17]
	s_barrier
	s_add_i32 s54, s54, 2
	s_add_u32 s22, s22, 0x100
	s_addc_u32 s23, s23, 0
	s_cmp_gt_u32 s54, 61
	s_cbranch_scc0 .LBB0_612
	s_and_b64 vcc, exec, s[16:17]
	s_cbranch_vccz .LBB0_615
	s_barrier

.LBB0_844:
	s_add_i32 s35, s52, 0xfffe8000
	s_and_b32 s34, s30, 0x100
	s_and_b32 s35, s35, 0x3e0000
	s_or_b32 s34, s34, s35
	s_add_u32 s53, s28, s34
	s_addc_u32 s55, s29, 0
	s_add_u32 s34, s30, 0x100
	s_addc_u32 s35, s31, 0
	s_add_i32 s37, s52, 0xffff8000
	s_and_b32 s36, s34, 0x100
	s_and_b32 s37, s37, 0x7e0000
	s_or_b32 s36, s37, s36
	s_add_u32 s36, s28, s36
	s_addc_u32 s37, s29, 0
	s_add_u32 s54, s49, s30
	s_addc_u32 s31, s50, s31
	s_add_i32 s38, s30, 0x180
	s_and_b32 s38, s38, 0x180
	s_and_b32 s39, s52, 0x7e0000
	s_or_b32 s38, s39, s38
	s_add_u32 s56, s28, s38
	s_addc_u32 s57, s29, 0
	s_cmpk_eq_i32 s30, 0x3f00
	s_cselect_b32 s39, s1, s37
	s_cselect_b32 s38, s21, s36
	s_cselect_b32 s37, s23, s31
	s_cselect_b32 s36, s22, s54
	s_cselect_b32 s31, s48, s57
	s_cselect_b32 s30, s27, s56
	s_add_i32 s56, 0, 0x10000
	v_add_u32_e32 v124, s56, v211
	ds_read_b128 v[104:107], v124
	ds_read_b128 v[108:111], v124 offset:1024
	ds_read_b128 v[120:123], v124 offset:2048
	ds_read_b128 v[124:127], v124 offset:3072
	ds_read_b128 v[144:147], v214
	ds_read_b128 v[148:151], v214 offset:1024
	ds_read_b128 v[152:155], v214 offset:2048
	ds_read_b128 v[156:159], v214 offset:3072
	s_add_u32 s54, s53, 0x10080
	s_addc_u32 s55, s55, 0
	s_add_i32 m0, s3, 0xc000
	ds_read_b128 v[160:163], v215
	ds_read_b128 v[164:167], v215 offset:1024
	ds_read_b128 v[168:171], v215 offset:2048
	ds_read_b128 v[172:175], v215 offset:3072
	ds_read_b128 v[176:179], v215 offset:4096
	ds_read_b128 v[180:183], v215 offset:5120
	ds_read_b128 v[192:195], v215 offset:6144
	ds_read_b128 v[196:199], v215 offset:7168
	global_load_lds_dwordx4 v184, s[54:55]
	s_add_i32 m0, s3, 0xe000
	s_nop 0
	global_load_lds_dwordx4 v188, s[54:55]
	s_waitcnt vmcnt(8)
	s_waitcnt lgkmcnt(0)
	s_barrier
	s_waitcnt lgkmcnt(0)
	v_mfma_f32_16x16x32_bf16 v[140:143], v[104:107], v[160:163], v[140:143]
	v_mfma_f32_16x16x32_bf16 v[140:143], v[108:111], v[164:167], v[140:143]
	v_mfma_f32_16x16x32_bf16 v[136:139], v[124:127], v[164:167], v[136:139]
	v_mfma_f32_16x16x32_bf16 v[136:139], v[120:123], v[160:163], v[136:139]
	v_mfma_f32_16x16x32_bf16 v[132:135], v[144:147], v[160:163], v[132:135]
	v_mfma_f32_16x16x32_bf16 v[132:135], v[148:151], v[164:167], v[132:135]
	v_mfma_f32_16x16x32_bf16 v[128:131], v[156:159], v[164:167], v[128:131]
	v_mfma_f32_16x16x32_bf16 v[128:131], v[152:155], v[160:163], v[128:131]
	v_mfma_f32_16x16x32_bf16 v[96:99], v[152:155], v[168:171], v[96:99]
	v_mfma_f32_16x16x32_bf16 v[96:99], v[156:159], v[172:175], v[96:99]
	v_mfma_f32_16x16x32_bf16 v[100:103], v[148:151], v[172:175], v[100:103]
	v_mfma_f32_16x16x32_bf16 v[100:103], v[144:147], v[168:171], v[100:103]
	v_mfma_f32_16x16x32_bf16 v[112:115], v[120:123], v[168:171], v[112:115]
	v_mfma_f32_16x16x32_bf16 v[112:115], v[124:127], v[172:175], v[112:115]
	v_mfma_f32_16x16x32_bf16 v[116:119], v[108:111], v[172:175], v[116:119]
	v_mfma_f32_16x16x32_bf16 v[116:119], v[104:107], v[168:171], v[116:119]
	v_mfma_f32_16x16x32_bf16 v[92:95], v[104:107], v[176:179], v[92:95]
	v_mfma_f32_16x16x32_bf16 v[92:95], v[108:111], v[180:183], v[92:95]
	v_mfma_f32_16x16x32_bf16 v[88:91], v[124:127], v[180:183], v[88:91]
	v_mfma_f32_16x16x32_bf16 v[88:91], v[120:123], v[176:179], v[88:91]
	v_mfma_f32_16x16x32_bf16 v[84:87], v[144:147], v[176:179], v[84:87]
	v_mfma_f32_16x16x32_bf16 v[84:87], v[148:151], v[180:183], v[84:87]
	v_mfma_f32_16x16x32_bf16 v[80:83], v[156:159], v[180:183], v[80:83]
	v_mfma_f32_16x16x32_bf16 v[80:83], v[152:155], v[176:179], v[80:83]
	v_mfma_f32_16x16x32_bf16 v[64:67], v[152:155], v[192:195], v[64:67]
	v_mfma_f32_16x16x32_bf16 v[64:67], v[156:159], v[196:199], v[64:67]
	v_mfma_f32_16x16x32_bf16 v[68:71], v[148:151], v[196:199], v[68:71]
	v_mfma_f32_16x16x32_bf16 v[68:71], v[144:147], v[192:195], v[68:71]
	v_mfma_f32_16x16x32_bf16 v[72:75], v[120:123], v[192:195], v[72:75]
	v_mfma_f32_16x16x32_bf16 v[72:75], v[124:127], v[196:199], v[72:75]
	v_mfma_f32_16x16x32_bf16 v[76:79], v[108:111], v[196:199], v[76:79]
	v_mfma_f32_16x16x32_bf16 v[76:79], v[104:107], v[192:195], v[76:79]
	s_barrier
	s_add_i32 s53, s56, s2
	v_lshl_add_u64 v[200:201], s[36:37], 0, v[186:187]
	s_mov_b32 m0, s53
	ds_read_b128 v[160:163], v215 offset:16384
	ds_read_b128 v[164:167], v215 offset:17408
	ds_read_b128 v[168:171], v215 offset:18432
	ds_read_b128 v[172:175], v215 offset:19456
	ds_read_b128 v[176:179], v215 offset:20480
	ds_read_b128 v[180:183], v215 offset:21504
	ds_read_b128 v[192:195], v215 offset:22528
	ds_read_b128 v[196:199], v215 offset:23552
	global_load_lds_dwordx4 v[200:201], off
	s_add_i32 m0, s53, 0x2000
	s_add_u32 s54, s36, 0x208000
	v_lshl_add_u64 v[202:203], s[36:37], 0, v[190:191]
	s_addc_u32 s55, s37, 0
	s_add_i32 s53, s45, s2
	global_load_lds_dwordx4 v[202:203], off
	s_mov_b32 m0, s53
	s_nop 0
	global_load_lds_dwordx4 v186, s[54:55]
	s_add_i32 m0, s53, 0x2000
	s_nop 0
	global_load_lds_dwordx4 v190, s[54:55]
	s_mov_b32 m0, s3
	s_nop 0
	global_load_lds_dwordx4 v184, s[38:39]
	s_mov_b32 m0, s33
	s_nop 0
	global_load_lds_dwordx4 v188, s[38:39]
	s_waitcnt vmcnt(8)
	s_waitcnt lgkmcnt(0)
	s_barrier
	s_waitcnt lgkmcnt(0)
	v_mfma_f32_16x16x32_bf16 v[60:63], v[104:107], v[160:163], v[60:63]
	v_mfma_f32_16x16x32_bf16 v[60:63], v[108:111], v[164:167], v[60:63]
	v_mfma_f32_16x16x32_bf16 v[56:59], v[124:127], v[164:167], v[56:59]
	v_mfma_f32_16x16x32_bf16 v[56:59], v[120:123], v[160:163], v[56:59]
	v_mfma_f32_16x16x32_bf16 v[52:55], v[144:147], v[160:163], v[52:55]
	v_mfma_f32_16x16x32_bf16 v[52:55], v[148:151], v[164:167], v[52:55]
	v_mfma_f32_16x16x32_bf16 v[48:51], v[156:159], v[164:167], v[48:51]
	v_mfma_f32_16x16x32_bf16 v[48:51], v[152:155], v[160:163], v[48:51]
	v_mfma_f32_16x16x32_bf16 v[32:35], v[152:155], v[168:171], v[32:35]
	v_mfma_f32_16x16x32_bf16 v[32:35], v[156:159], v[172:175], v[32:35]
	v_mfma_f32_16x16x32_bf16 v[36:39], v[148:151], v[172:175], v[36:39]
	v_mfma_f32_16x16x32_bf16 v[36:39], v[144:147], v[168:171], v[36:39]
	v_mfma_f32_16x16x32_bf16 v[40:43], v[120:123], v[168:171], v[40:43]
	v_mfma_f32_16x16x32_bf16 v[40:43], v[124:127], v[172:175], v[40:43]
	v_mfma_f32_16x16x32_bf16 v[44:47], v[108:111], v[172:175], v[44:47]
	v_mfma_f32_16x16x32_bf16 v[44:47], v[104:107], v[168:171], v[44:47]
	v_mfma_f32_16x16x32_bf16 v[28:31], v[104:107], v[176:179], v[28:31]
	v_mfma_f32_16x16x32_bf16 v[28:31], v[108:111], v[180:183], v[28:31]
	v_mfma_f32_16x16x32_bf16 v[24:27], v[124:127], v[180:183], v[24:27]
	v_mfma_f32_16x16x32_bf16 v[24:27], v[120:123], v[176:179], v[24:27]
	v_mfma_f32_16x16x32_bf16 v[20:23], v[144:147], v[176:179], v[20:23]
	v_mfma_f32_16x16x32_bf16 v[20:23], v[148:151], v[180:183], v[20:23]
	v_mfma_f32_16x16x32_bf16 v[16:19], v[156:159], v[180:183], v[16:19]
	v_mfma_f32_16x16x32_bf16 v[16:19], v[152:155], v[176:179], v[16:19]
	v_mfma_f32_16x16x32_bf16 v[0:3], v[152:155], v[192:195], v[0:3]
	v_mfma_f32_16x16x32_bf16 v[0:3], v[156:159], v[196:199], v[0:3]
	v_mfma_f32_16x16x32_bf16 v[4:7], v[148:151], v[196:199], v[4:7]
	v_mfma_f32_16x16x32_bf16 v[4:7], v[144:147], v[192:195], v[4:7]
	v_mfma_f32_16x16x32_bf16 v[8:11], v[120:123], v[192:195], v[8:11]
	v_mfma_f32_16x16x32_bf16 v[8:11], v[124:127], v[196:199], v[8:11]
	v_mfma_f32_16x16x32_bf16 v[12:15], v[108:111], v[196:199], v[12:15]
	v_mfma_f32_16x16x32_bf16 v[12:15], v[104:107], v[192:195], v[12:15]
	s_barrier
	s_add_i32 s53, 0, 0x18000
	s_add_i32 s54, 0, 0x1c000
	v_add_u32_e32 v124, s53, v211
	v_add_u32_e32 v156, s54, v211
	ds_read_b128 v[104:107], v124
	ds_read_b128 v[108:111], v124 offset:1024
	ds_read_b128 v[120:123], v124 offset:2048
	ds_read_b128 v[124:127], v124 offset:3072
	ds_read_b128 v[144:147], v156
	ds_read_b128 v[148:151], v156 offset:1024
	ds_read_b128 v[152:155], v156 offset:2048
	ds_read_b128 v[156:159], v156 offset:3072
	s_add_u32 s38, s38, 0x10000
	s_addc_u32 s39, s39, 0
	s_mov_b32 m0, s40
	ds_read_b128 v[160:163], v215 offset:32768
	ds_read_b128 v[164:167], v215 offset:33792
	ds_read_b128 v[168:171], v215 offset:34816
	ds_read_b128 v[172:175], v215 offset:35840
	ds_read_b128 v[176:179], v215 offset:36864
	ds_read_b128 v[180:183], v215 offset:37888
	ds_read_b128 v[192:195], v215 offset:38912
	ds_read_b128 v[196:199], v215 offset:39936
	global_load_lds_dwordx4 v184, s[38:39]
	v_lshl_add_u64 v[204:205], s[38:39], 0, v[188:189]
	s_mov_b32 m0, s41
	s_nop 0
	global_load_lds_dwordx4 v[204:205], off
	s_waitcnt vmcnt(8)
	s_waitcnt lgkmcnt(0)
	s_barrier
	s_waitcnt lgkmcnt(0)
	v_mfma_f32_16x16x32_bf16 v[140:143], v[104:107], v[160:163], v[140:143]
	v_mfma_f32_16x16x32_bf16 v[140:143], v[108:111], v[164:167], v[140:143]
	v_mfma_f32_16x16x32_bf16 v[136:139], v[124:127], v[164:167], v[136:139]
	v_mfma_f32_16x16x32_bf16 v[136:139], v[120:123], v[160:163], v[136:139]
	v_mfma_f32_16x16x32_bf16 v[132:135], v[144:147], v[160:163], v[132:135]
	v_mfma_f32_16x16x32_bf16 v[132:135], v[148:151], v[164:167], v[132:135]
	v_mfma_f32_16x16x32_bf16 v[128:131], v[156:159], v[164:167], v[128:131]
	v_mfma_f32_16x16x32_bf16 v[128:131], v[152:155], v[160:163], v[128:131]
	v_mfma_f32_16x16x32_bf16 v[96:99], v[152:155], v[168:171], v[96:99]
	v_mfma_f32_16x16x32_bf16 v[96:99], v[156:159], v[172:175], v[96:99]
	v_mfma_f32_16x16x32_bf16 v[100:103], v[148:151], v[172:175], v[100:103]
	v_mfma_f32_16x16x32_bf16 v[100:103], v[144:147], v[168:171], v[100:103]
	v_mfma_f32_16x16x32_bf16 v[112:115], v[120:123], v[168:171], v[112:115]
	v_mfma_f32_16x16x32_bf16 v[112:115], v[124:127], v[172:175], v[112:115]
	v_mfma_f32_16x16x32_bf16 v[116:119], v[108:111], v[172:175], v[116:119]
	v_mfma_f32_16x16x32_bf16 v[116:119], v[104:107], v[168:171], v[116:119]
	v_mfma_f32_16x16x32_bf16 v[92:95], v[104:107], v[176:179], v[92:95]
	v_mfma_f32_16x16x32_bf16 v[92:95], v[108:111], v[180:183], v[92:95]
	v_mfma_f32_16x16x32_bf16 v[88:91], v[124:127], v[180:183], v[88:91]
	v_mfma_f32_16x16x32_bf16 v[88:91], v[120:123], v[176:179], v[88:91]
	v_mfma_f32_16x16x32_bf16 v[84:87], v[144:147], v[176:179], v[84:87]
	v_mfma_f32_16x16x32_bf16 v[84:87], v[148:151], v[180:183], v[84:87]
	v_mfma_f32_16x16x32_bf16 v[80:83], v[156:159], v[180:183], v[80:83]
	v_mfma_f32_16x16x32_bf16 v[80:83], v[152:155], v[176:179], v[80:83]
	v_mfma_f32_16x16x32_bf16 v[64:67], v[152:155], v[192:195], v[64:67]
	v_mfma_f32_16x16x32_bf16 v[64:67], v[156:159], v[196:199], v[64:67]
	v_mfma_f32_16x16x32_bf16 v[68:71], v[148:151], v[196:199], v[68:71]
	v_mfma_f32_16x16x32_bf16 v[68:71], v[144:147], v[192:195], v[68:71]
	v_mfma_f32_16x16x32_bf16 v[72:75], v[120:123], v[192:195], v[72:75]
	v_mfma_f32_16x16x32_bf16 v[72:75], v[124:127], v[196:199], v[72:75]
	v_mfma_f32_16x16x32_bf16 v[76:79], v[108:111], v[196:199], v[76:79]
	v_mfma_f32_16x16x32_bf16 v[76:79], v[104:107], v[192:195], v[76:79]
	s_barrier
	s_add_i32 s38, s53, s2
	v_lshl_add_u64 v[200:201], v[200:201], 0, s[16:17]
	s_mov_b32 m0, s38
	ds_read_b128 v[160:163], v215 offset:49152
	ds_read_b128 v[164:167], v215 offset:50176
	ds_read_b128 v[168:171], v215 offset:51200
	ds_read_b128 v[172:175], v215 offset:52224
	ds_read_b128 v[176:179], v215 offset:53248
	ds_read_b128 v[180:183], v215 offset:54272
	ds_read_b128 v[192:195], v215 offset:55296
	ds_read_b128 v[196:199], v215 offset:56320
	global_load_lds_dwordx4 v[200:201], off
	s_add_i32 m0, s38, 0x2000
	s_add_u32 s36, s36, 0x208080
	v_lshl_add_u64 v[200:201], v[202:203], 0, s[16:17]
	s_addc_u32 s37, s37, 0
	s_add_i32 s38, s54, s2
	global_load_lds_dwordx4 v[200:201], off
	s_mov_b32 m0, s38
	s_nop 0
	global_load_lds_dwordx4 v186, s[36:37]
	s_add_i32 m0, s38, 0x2000
	s_nop 0
	global_load_lds_dwordx4 v190, s[36:37]
	s_mov_b32 m0, s43
	s_nop 0
	global_load_lds_dwordx4 v184, s[30:31]
	v_lshl_add_u64 v[200:201], s[30:31], 0, v[188:189]
	s_mov_b32 m0, s44
	s_nop 0
	global_load_lds_dwordx4 v[200:201], off
	s_waitcnt vmcnt(8)
	s_waitcnt lgkmcnt(0)
	s_barrier
	s_waitcnt lgkmcnt(0)
	v_mfma_f32_16x16x32_bf16 v[60:63], v[104:107], v[160:163], v[60:63]
	v_mfma_f32_16x16x32_bf16 v[60:63], v[108:111], v[164:167], v[60:63]
	v_mfma_f32_16x16x32_bf16 v[56:59], v[124:127], v[164:167], v[56:59]
	v_mfma_f32_16x16x32_bf16 v[56:59], v[120:123], v[160:163], v[56:59]
	v_mfma_f32_16x16x32_bf16 v[52:55], v[144:147], v[160:163], v[52:55]
	v_mfma_f32_16x16x32_bf16 v[52:55], v[148:151], v[164:167], v[52:55]
	v_mfma_f32_16x16x32_bf16 v[48:51], v[156:159], v[164:167], v[48:51]
	v_mfma_f32_16x16x32_bf16 v[48:51], v[152:155], v[160:163], v[48:51]
	v_mfma_f32_16x16x32_bf16 v[32:35], v[152:155], v[168:171], v[32:35]
	v_mfma_f32_16x16x32_bf16 v[32:35], v[156:159], v[172:175], v[32:35]
	v_mfma_f32_16x16x32_bf16 v[36:39], v[148:151], v[172:175], v[36:39]
	v_mfma_f32_16x16x32_bf16 v[36:39], v[144:147], v[168:171], v[36:39]
	v_mfma_f32_16x16x32_bf16 v[40:43], v[120:123], v[168:171], v[40:43]
	v_mfma_f32_16x16x32_bf16 v[40:43], v[124:127], v[172:175], v[40:43]
	v_mfma_f32_16x16x32_bf16 v[44:47], v[108:111], v[172:175], v[44:47]
	v_mfma_f32_16x16x32_bf16 v[44:47], v[104:107], v[168:171], v[44:47]
	v_mfma_f32_16x16x32_bf16 v[28:31], v[104:107], v[176:179], v[28:31]
	v_mfma_f32_16x16x32_bf16 v[28:31], v[108:111], v[180:183], v[28:31]
	v_mfma_f32_16x16x32_bf16 v[24:27], v[124:127], v[180:183], v[24:27]
	v_mfma_f32_16x16x32_bf16 v[24:27], v[120:123], v[176:179], v[24:27]
	v_mfma_f32_16x16x32_bf16 v[20:23], v[144:147], v[176:179], v[20:23]
	v_mfma_f32_16x16x32_bf16 v[20:23], v[148:151], v[180:183], v[20:23]
	v_mfma_f32_16x16x32_bf16 v[16:19], v[156:159], v[180:183], v[16:19]
	v_mfma_f32_16x16x32_bf16 v[16:19], v[152:155], v[176:179], v[16:19]
	v_mfma_f32_16x16x32_bf16 v[0:3], v[152:155], v[192:195], v[0:3]
	v_mfma_f32_16x16x32_bf16 v[0:3], v[156:159], v[196:199], v[0:3]
	v_mfma_f32_16x16x32_bf16 v[4:7], v[148:151], v[196:199], v[4:7]
	v_mfma_f32_16x16x32_bf16 v[4:7], v[144:147], v[192:195], v[4:7]
	v_mfma_f32_16x16x32_bf16 v[8:11], v[120:123], v[192:195], v[8:11]
	v_mfma_f32_16x16x32_bf16 v[8:11], v[124:127], v[196:199], v[8:11]
	v_mfma_f32_16x16x32_bf16 v[12:15], v[108:111], v[196:199], v[12:15]
	v_mfma_f32_16x16x32_bf16 v[12:15], v[104:107], v[192:195], v[12:15]
	s_barrier
	s_add_i32 s51, s51, 2
	s_add_i32 s52, s52, 0x10000
	s_cmpk_gt_u32 s51, 0x7d
	s_mov_b64 s[30:31], s[34:35]
	s_cbranch_scc0 .LBB0_844
	s_and_b64 vcc, exec, s[18:19]
	s_cbranch_vccz .LBB0_847
	s_barrier
